# P1 HGRN2 tile epilogue by hand: eight d-columns per 16-step block processed together (stage-ordered, no s_nop), packed f32 ops, stores overlapped with the next block
# speedup vs baseline: 1.0112x; 1.0059x over previous
.LBB0_162:
	s_lshl_b32 s0, s72, 7
	s_ashr_i32 s1, s0, 31
	s_lshl_b64 s[2:3], s[0:1], 2
	s_add_u32 s44, s51, s2
	s_addc_u32 s45, s52, s3
	v_ashrrev_i32_e32 v5, 31, v4
	v_lshlrev_b64 v[4:5], 2, v[4:5]
	v_lshl_add_u64 v[138:139], s[44:45], 0, v[4:5]
	global_load_dwordx4 v[134:137], v[138:139], off offset:16
	s_nop 0
	global_load_dwordx4 v[138:141], v[138:139], off
	v_lshl_add_u32 v142, v150, 4, v3
	v_and_b32_e32 v143, 3, v3
	v_cmp_eq_u32_e64 s[90:91], 15, v3
	s_lshl_b64 s[0:1], s[0:1], 1
	s_add_u32 s44, s22, s0
	s_addc_u32 s45, s23, s1
	s_lshl_b32 s4, s50, 1
	v_lshlrev_b32_e32 v144, 6, v143
	s_add_u32 s0, s26, s0
	s_addc_u32 s1, s27, s1
	v_and_or_b32 v148, v142, -4, v144
	v_lshl_or_b32 v144, v143, 4, s4
	v_mov_b32_e32 v145, v2
	v_ashrrev_i32_e32 v149, 2, v142
	v_lshl_add_u64 v[142:143], s[44:45], 0, v[144:145]
	v_lshl_add_u64 v[144:145], s[0:1], 0, v[144:145]
	s_add_u32 s0, s97, s2
	s_addc_u32 s1, s6, s3
	v_lshl_add_u64 v[146:147], s[0:1], 0, v[4:5]
	s_mov_b32 s84, 0xbfb8aa3b
	s_mov_b32 s85, s84
	s_mov_b32 s86, 1.0
	s_mov_b32 s87, 1.0
	v_add_u32_e32 v4, s43, v149
	v_pk_mul_f32 v[150:151], v[130:131], s[84:85] op_sel_hi:[1,0]
	v_pk_mul_f32 v[152:153], v[132:133], s[84:85] op_sel_hi:[1,0]
	v_pk_mul_f32 v[154:155], v[98:99], s[84:85] op_sel_hi:[1,0]
	v_pk_mul_f32 v[156:157], v[100:101], s[84:85] op_sel_hi:[1,0]
	v_exp_f32_e32 v150, v150
	v_exp_f32_e32 v151, v151
	v_exp_f32_e32 v152, v152
	v_exp_f32_e32 v153, v153
	v_exp_f32_e32 v154, v154
	v_exp_f32_e32 v155, v155
	v_exp_f32_e32 v156, v156
	v_exp_f32_e32 v157, v157
	v_pk_add_f32 v[150:151], v[150:151], s[86:87] op_sel_hi:[1,0]
	v_pk_add_f32 v[152:153], v[152:153], s[86:87] op_sel_hi:[1,0]
	v_pk_add_f32 v[154:155], v[154:155], s[86:87] op_sel_hi:[1,0]
	v_pk_add_f32 v[156:157], v[156:157], s[86:87] op_sel_hi:[1,0]
	v_rcp_f32_e32 v150, v150
	v_rcp_f32_e32 v151, v151
	v_rcp_f32_e32 v152, v152
	v_rcp_f32_e32 v153, v153
	v_rcp_f32_e32 v154, v154
	v_rcp_f32_e32 v155, v155
	v_rcp_f32_e32 v156, v156
	v_rcp_f32_e32 v157, v157
	s_waitcnt vmcnt(0)
	v_pk_add_f32 v[174:175], v[138:139], s[86:87] op_sel_hi:[1,0] neg_lo:[1,0] neg_hi:[1,0]
	v_pk_add_f32 v[176:177], v[140:141], s[86:87] op_sel_hi:[1,0] neg_lo:[1,0] neg_hi:[1,0]
	v_pk_add_f32 v[178:179], v[134:135], s[86:87] op_sel_hi:[1,0] neg_lo:[1,0] neg_hi:[1,0]
	v_pk_add_f32 v[180:181], v[136:137], s[86:87] op_sel_hi:[1,0] neg_lo:[1,0] neg_hi:[1,0]
	v_pk_fma_f32 v[150:151], v[150:151], v[174:175], v[138:139]
	v_pk_fma_f32 v[152:153], v[152:153], v[176:177], v[140:141]
	v_pk_fma_f32 v[154:155], v[154:155], v[178:179], v[134:135]
	v_pk_fma_f32 v[156:157], v[156:157], v[180:181], v[136:137]
	v_log_f32_e32 v158, v150
	v_log_f32_e32 v159, v151
	v_log_f32_e32 v160, v152
	v_log_f32_e32 v161, v153
	v_log_f32_e32 v162, v154
	v_log_f32_e32 v163, v155
	v_log_f32_e32 v164, v156
	v_log_f32_e32 v165, v157
	v_add_f32_dpp v158, v158, v158 row_shr:1 row_mask:0xf bank_mask:0xf bound_ctrl:1
	v_add_f32_dpp v159, v159, v159 row_shr:1 row_mask:0xf bank_mask:0xf bound_ctrl:1
	v_add_f32_dpp v160, v160, v160 row_shr:1 row_mask:0xf bank_mask:0xf bound_ctrl:1
	v_add_f32_dpp v161, v161, v161 row_shr:1 row_mask:0xf bank_mask:0xf bound_ctrl:1
	v_add_f32_dpp v162, v162, v162 row_shr:1 row_mask:0xf bank_mask:0xf bound_ctrl:1
	v_add_f32_dpp v163, v163, v163 row_shr:1 row_mask:0xf bank_mask:0xf bound_ctrl:1
	v_add_f32_dpp v164, v164, v164 row_shr:1 row_mask:0xf bank_mask:0xf bound_ctrl:1
	v_add_f32_dpp v165, v165, v165 row_shr:1 row_mask:0xf bank_mask:0xf bound_ctrl:1
	v_add_f32_dpp v158, v158, v158 row_shr:2 row_mask:0xf bank_mask:0xf bound_ctrl:1
	v_add_f32_dpp v159, v159, v159 row_shr:2 row_mask:0xf bank_mask:0xf bound_ctrl:1
	v_add_f32_dpp v160, v160, v160 row_shr:2 row_mask:0xf bank_mask:0xf bound_ctrl:1
	v_add_f32_dpp v161, v161, v161 row_shr:2 row_mask:0xf bank_mask:0xf bound_ctrl:1
	v_add_f32_dpp v162, v162, v162 row_shr:2 row_mask:0xf bank_mask:0xf bound_ctrl:1
	v_add_f32_dpp v163, v163, v163 row_shr:2 row_mask:0xf bank_mask:0xf bound_ctrl:1
	v_add_f32_dpp v164, v164, v164 row_shr:2 row_mask:0xf bank_mask:0xf bound_ctrl:1
	v_add_f32_dpp v165, v165, v165 row_shr:2 row_mask:0xf bank_mask:0xf bound_ctrl:1
	v_add_f32_dpp v158, v158, v158 row_shr:4 row_mask:0xf bank_mask:0xf bound_ctrl:1
	v_add_f32_dpp v159, v159, v159 row_shr:4 row_mask:0xf bank_mask:0xf bound_ctrl:1
	v_add_f32_dpp v160, v160, v160 row_shr:4 row_mask:0xf bank_mask:0xf bound_ctrl:1
	v_add_f32_dpp v161, v161, v161 row_shr:4 row_mask:0xf bank_mask:0xf bound_ctrl:1
	v_add_f32_dpp v162, v162, v162 row_shr:4 row_mask:0xf bank_mask:0xf bound_ctrl:1
	v_add_f32_dpp v163, v163, v163 row_shr:4 row_mask:0xf bank_mask:0xf bound_ctrl:1
	v_add_f32_dpp v164, v164, v164 row_shr:4 row_mask:0xf bank_mask:0xf bound_ctrl:1
	v_add_f32_dpp v165, v165, v165 row_shr:4 row_mask:0xf bank_mask:0xf bound_ctrl:1
	v_add_f32_dpp v158, v158, v158 row_shr:8 row_mask:0xf bank_mask:0xf bound_ctrl:1
	v_add_f32_dpp v159, v159, v159 row_shr:8 row_mask:0xf bank_mask:0xf bound_ctrl:1
	v_add_f32_dpp v160, v160, v160 row_shr:8 row_mask:0xf bank_mask:0xf bound_ctrl:1
	v_add_f32_dpp v161, v161, v161 row_shr:8 row_mask:0xf bank_mask:0xf bound_ctrl:1
	v_add_f32_dpp v162, v162, v162 row_shr:8 row_mask:0xf bank_mask:0xf bound_ctrl:1
	v_add_f32_dpp v163, v163, v163 row_shr:8 row_mask:0xf bank_mask:0xf bound_ctrl:1
	v_add_f32_dpp v164, v164, v164 row_shr:8 row_mask:0xf bank_mask:0xf bound_ctrl:1
	v_add_f32_dpp v165, v165, v165 row_shr:8 row_mask:0xf bank_mask:0xf bound_ctrl:1
	v_exp_f32_e64 v174, -v158
	v_exp_f32_e64 v175, -v159
	v_exp_f32_e64 v176, -v160
	v_exp_f32_e64 v177, -v161
	v_exp_f32_e64 v178, -v162
	v_exp_f32_e64 v179, -v163
	v_exp_f32_e64 v180, -v164
	v_exp_f32_e64 v181, -v165
	v_pk_mul_f32 v[182:183], v[102:103], s[84:85] op_sel_hi:[1,0]
	v_pk_mul_f32 v[184:185], v[104:105], s[84:85] op_sel_hi:[1,0]
	v_pk_mul_f32 v[186:187], v[70:71], s[84:85] op_sel_hi:[1,0]
	v_pk_mul_f32 v[188:189], v[72:73], s[84:85] op_sel_hi:[1,0]
	v_exp_f32_e32 v182, v182
	v_exp_f32_e32 v183, v183
	v_exp_f32_e32 v184, v184
	v_exp_f32_e32 v185, v185
	v_exp_f32_e32 v186, v186
	v_exp_f32_e32 v187, v187
	v_exp_f32_e32 v188, v188
	v_exp_f32_e32 v189, v189
	v_pk_add_f32 v[182:183], v[182:183], s[86:87] op_sel_hi:[1,0]
	v_pk_add_f32 v[184:185], v[184:185], s[86:87] op_sel_hi:[1,0]
	v_pk_add_f32 v[186:187], v[186:187], s[86:87] op_sel_hi:[1,0]
	v_pk_add_f32 v[188:189], v[188:189], s[86:87] op_sel_hi:[1,0]
	v_pk_mul_f32 v[182:183], v[182:183], v[174:175]
	v_pk_mul_f32 v[184:185], v[184:185], v[176:177]
	v_pk_mul_f32 v[186:187], v[186:187], v[178:179]
	v_pk_mul_f32 v[188:189], v[188:189], v[180:181]
	v_rcp_f32_e32 v182, v182
	v_rcp_f32_e32 v183, v183
	v_rcp_f32_e32 v184, v184
	v_rcp_f32_e32 v185, v185
	v_rcp_f32_e32 v186, v186
	v_rcp_f32_e32 v187, v187
	v_rcp_f32_e32 v188, v188
	v_rcp_f32_e32 v189, v189
	v_pk_add_f32 v[150:151], v[150:151], s[86:87] op_sel_hi:[1,0] neg_lo:[1,0] neg_hi:[1,0]
	v_pk_add_f32 v[152:153], v[152:153], s[86:87] op_sel_hi:[1,0] neg_lo:[1,0] neg_hi:[1,0]
	v_pk_add_f32 v[154:155], v[154:155], s[86:87] op_sel_hi:[1,0] neg_lo:[1,0] neg_hi:[1,0]
	v_pk_add_f32 v[156:157], v[156:157], s[86:87] op_sel_hi:[1,0] neg_lo:[1,0] neg_hi:[1,0]
	v_pk_mul_f32 v[150:151], v[150:151], v[174:175]
	v_pk_mul_f32 v[152:153], v[152:153], v[176:177]
	v_pk_mul_f32 v[154:155], v[154:155], v[178:179]
	v_pk_mul_f32 v[156:157], v[156:157], v[180:181]
	v_pk_mul_f32 v[182:183], v[102:103], v[182:183]
	v_pk_mul_f32 v[184:185], v[104:105], v[184:185]
	v_pk_mul_f32 v[186:187], v[70:71], v[186:187]
	v_pk_mul_f32 v[188:189], v[72:73], v[188:189]
	v_cvt_pk_bf16_f32 v174, v182, v183
	v_cvt_pk_bf16_f32 v175, v184, v185
	v_cvt_pk_bf16_f32 v176, v186, v187
	v_cvt_pk_bf16_f32 v177, v188, v189
	v_cvt_pk_bf16_f32 v178, v150, v151
	v_cvt_pk_bf16_f32 v179, v152, v153
	v_cvt_pk_bf16_f32 v180, v154, v155
	v_cvt_pk_bf16_f32 v181, v156, v157
	ds_bpermute_b32 v190, v148, v174
	ds_bpermute_b32 v191, v148, v175
	ds_bpermute_b32 v192, v148, v176
	ds_bpermute_b32 v193, v148, v177
	ds_bpermute_b32 v194, v148, v178
	ds_bpermute_b32 v195, v148, v179
	ds_bpermute_b32 v196, v148, v180
	ds_bpermute_b32 v197, v148, v181
	v_pk_mul_f32 v[150:151], v[126:127], s[84:85] op_sel_hi:[1,0]
	v_pk_mul_f32 v[152:153], v[128:129], s[84:85] op_sel_hi:[1,0]
	v_pk_mul_f32 v[154:155], v[94:95], s[84:85] op_sel_hi:[1,0]
	v_pk_mul_f32 v[156:157], v[96:97], s[84:85] op_sel_hi:[1,0]
	v_exp_f32_e32 v150, v150
	v_exp_f32_e32 v151, v151
	v_exp_f32_e32 v152, v152
	v_exp_f32_e32 v153, v153
	v_exp_f32_e32 v154, v154
	v_exp_f32_e32 v155, v155
	v_exp_f32_e32 v156, v156
	v_exp_f32_e32 v157, v157
	v_pk_add_f32 v[150:151], v[150:151], s[86:87] op_sel_hi:[1,0]
	v_pk_add_f32 v[152:153], v[152:153], s[86:87] op_sel_hi:[1,0]
	v_pk_add_f32 v[154:155], v[154:155], s[86:87] op_sel_hi:[1,0]
	v_pk_add_f32 v[156:157], v[156:157], s[86:87] op_sel_hi:[1,0]
	v_rcp_f32_e32 v150, v150
	v_rcp_f32_e32 v151, v151
	v_rcp_f32_e32 v152, v152
	v_rcp_f32_e32 v153, v153
	v_rcp_f32_e32 v154, v154
	v_rcp_f32_e32 v155, v155
	v_rcp_f32_e32 v156, v156
	v_rcp_f32_e32 v157, v157
	v_mov_b32_e32 v220, v4
	v_ashrrev_i32_e32 v221, 31, v220
	v_lshlrev_b64 v[222:223], 12, v[220:221]
	v_lshlrev_b64 v[224:225], 11, v[220:221]
	v_lshl_add_u64 v[222:223], v[142:143], 0, v[222:223]
	v_lshl_add_u64 v[224:225], v[144:145], 0, v[224:225]
	s_waitcnt lgkmcnt(0)
	global_store_dwordx4 v[222:223], v[190:193], off nt
	global_store_dwordx4 v[224:225], v[194:197], off nt
	v_pk_add_f32 v[174:175], v[138:139], s[86:87] op_sel_hi:[1,0] neg_lo:[1,0] neg_hi:[1,0]
	v_pk_add_f32 v[176:177], v[140:141], s[86:87] op_sel_hi:[1,0] neg_lo:[1,0] neg_hi:[1,0]
	v_pk_add_f32 v[178:179], v[134:135], s[86:87] op_sel_hi:[1,0] neg_lo:[1,0] neg_hi:[1,0]
	v_pk_add_f32 v[180:181], v[136:137], s[86:87] op_sel_hi:[1,0] neg_lo:[1,0] neg_hi:[1,0]
	v_pk_fma_f32 v[150:151], v[150:151], v[174:175], v[138:139]
	v_pk_fma_f32 v[152:153], v[152:153], v[176:177], v[140:141]
	v_pk_fma_f32 v[154:155], v[154:155], v[178:179], v[134:135]
	v_pk_fma_f32 v[156:157], v[156:157], v[180:181], v[136:137]
	v_log_f32_e32 v166, v150
	v_log_f32_e32 v167, v151
	v_log_f32_e32 v168, v152
	v_log_f32_e32 v169, v153
	v_log_f32_e32 v170, v154
	v_log_f32_e32 v171, v155
	v_log_f32_e32 v172, v156
	v_log_f32_e32 v173, v157
	v_add_f32_dpp v166, v166, v166 row_shr:1 row_mask:0xf bank_mask:0xf bound_ctrl:1
	v_add_f32_dpp v167, v167, v167 row_shr:1 row_mask:0xf bank_mask:0xf bound_ctrl:1
	v_add_f32_dpp v168, v168, v168 row_shr:1 row_mask:0xf bank_mask:0xf bound_ctrl:1
	v_add_f32_dpp v169, v169, v169 row_shr:1 row_mask:0xf bank_mask:0xf bound_ctrl:1
	v_add_f32_dpp v170, v170, v170 row_shr:1 row_mask:0xf bank_mask:0xf bound_ctrl:1
	v_add_f32_dpp v171, v171, v171 row_shr:1 row_mask:0xf bank_mask:0xf bound_ctrl:1
	v_add_f32_dpp v172, v172, v172 row_shr:1 row_mask:0xf bank_mask:0xf bound_ctrl:1
	v_add_f32_dpp v173, v173, v173 row_shr:1 row_mask:0xf bank_mask:0xf bound_ctrl:1
	v_add_f32_dpp v166, v166, v166 row_shr:2 row_mask:0xf bank_mask:0xf bound_ctrl:1
	v_add_f32_dpp v167, v167, v167 row_shr:2 row_mask:0xf bank_mask:0xf bound_ctrl:1
	v_add_f32_dpp v168, v168, v168 row_shr:2 row_mask:0xf bank_mask:0xf bound_ctrl:1
	v_add_f32_dpp v169, v169, v169 row_shr:2 row_mask:0xf bank_mask:0xf bound_ctrl:1
	v_add_f32_dpp v170, v170, v170 row_shr:2 row_mask:0xf bank_mask:0xf bound_ctrl:1
	v_add_f32_dpp v171, v171, v171 row_shr:2 row_mask:0xf bank_mask:0xf bound_ctrl:1
	v_add_f32_dpp v172, v172, v172 row_shr:2 row_mask:0xf bank_mask:0xf bound_ctrl:1
	v_add_f32_dpp v173, v173, v173 row_shr:2 row_mask:0xf bank_mask:0xf bound_ctrl:1
	v_add_f32_dpp v166, v166, v166 row_shr:4 row_mask:0xf bank_mask:0xf bound_ctrl:1
	v_add_f32_dpp v167, v167, v167 row_shr:4 row_mask:0xf bank_mask:0xf bound_ctrl:1
	v_add_f32_dpp v168, v168, v168 row_shr:4 row_mask:0xf bank_mask:0xf bound_ctrl:1
	v_add_f32_dpp v169, v169, v169 row_shr:4 row_mask:0xf bank_mask:0xf bound_ctrl:1
	v_add_f32_dpp v170, v170, v170 row_shr:4 row_mask:0xf bank_mask:0xf bound_ctrl:1
	v_add_f32_dpp v171, v171, v171 row_shr:4 row_mask:0xf bank_mask:0xf bound_ctrl:1
	v_add_f32_dpp v172, v172, v172 row_shr:4 row_mask:0xf bank_mask:0xf bound_ctrl:1
	v_add_f32_dpp v173, v173, v173 row_shr:4 row_mask:0xf bank_mask:0xf bound_ctrl:1
	v_add_f32_dpp v166, v166, v166 row_shr:8 row_mask:0xf bank_mask:0xf bound_ctrl:1
	v_add_f32_dpp v167, v167, v167 row_shr:8 row_mask:0xf bank_mask:0xf bound_ctrl:1
	v_add_f32_dpp v168, v168, v168 row_shr:8 row_mask:0xf bank_mask:0xf bound_ctrl:1
	v_add_f32_dpp v169, v169, v169 row_shr:8 row_mask:0xf bank_mask:0xf bound_ctrl:1
	v_add_f32_dpp v170, v170, v170 row_shr:8 row_mask:0xf bank_mask:0xf bound_ctrl:1
	v_add_f32_dpp v171, v171, v171 row_shr:8 row_mask:0xf bank_mask:0xf bound_ctrl:1
	v_add_f32_dpp v172, v172, v172 row_shr:8 row_mask:0xf bank_mask:0xf bound_ctrl:1
	v_add_f32_dpp v173, v173, v173 row_shr:8 row_mask:0xf bank_mask:0xf bound_ctrl:1
	v_add_f32_dpp v166, v158, v166 row_newbcast:15 row_mask:0xf bank_mask:0xf bound_ctrl:1
	v_add_f32_dpp v167, v159, v167 row_newbcast:15 row_mask:0xf bank_mask:0xf bound_ctrl:1
	v_add_f32_dpp v168, v160, v168 row_newbcast:15 row_mask:0xf bank_mask:0xf bound_ctrl:1
	v_add_f32_dpp v169, v161, v169 row_newbcast:15 row_mask:0xf bank_mask:0xf bound_ctrl:1
	v_add_f32_dpp v170, v162, v170 row_newbcast:15 row_mask:0xf bank_mask:0xf bound_ctrl:1
	v_add_f32_dpp v171, v163, v171 row_newbcast:15 row_mask:0xf bank_mask:0xf bound_ctrl:1
	v_add_f32_dpp v172, v164, v172 row_newbcast:15 row_mask:0xf bank_mask:0xf bound_ctrl:1
	v_add_f32_dpp v173, v165, v173 row_newbcast:15 row_mask:0xf bank_mask:0xf bound_ctrl:1
	v_exp_f32_e64 v174, -v166
	v_exp_f32_e64 v175, -v167
	v_exp_f32_e64 v176, -v168
	v_exp_f32_e64 v177, -v169
	v_exp_f32_e64 v178, -v170
	v_exp_f32_e64 v179, -v171
	v_exp_f32_e64 v180, -v172
	v_exp_f32_e64 v181, -v173
	v_pk_mul_f32 v[182:183], v[114:115], s[84:85] op_sel_hi:[1,0]
	v_pk_mul_f32 v[184:185], v[116:117], s[84:85] op_sel_hi:[1,0]
	v_pk_mul_f32 v[186:187], v[82:83], s[84:85] op_sel_hi:[1,0]
	v_pk_mul_f32 v[188:189], v[84:85], s[84:85] op_sel_hi:[1,0]
	v_exp_f32_e32 v182, v182
	v_exp_f32_e32 v183, v183
	v_exp_f32_e32 v184, v184
	v_exp_f32_e32 v185, v185
	v_exp_f32_e32 v186, v186
	v_exp_f32_e32 v187, v187
	v_exp_f32_e32 v188, v188
	v_exp_f32_e32 v189, v189
	v_pk_add_f32 v[182:183], v[182:183], s[86:87] op_sel_hi:[1,0]
	v_pk_add_f32 v[184:185], v[184:185], s[86:87] op_sel_hi:[1,0]
	v_pk_add_f32 v[186:187], v[186:187], s[86:87] op_sel_hi:[1,0]
	v_pk_add_f32 v[188:189], v[188:189], s[86:87] op_sel_hi:[1,0]
	v_pk_mul_f32 v[182:183], v[182:183], v[174:175]
	v_pk_mul_f32 v[184:185], v[184:185], v[176:177]
	v_pk_mul_f32 v[186:187], v[186:187], v[178:179]
	v_pk_mul_f32 v[188:189], v[188:189], v[180:181]
	v_rcp_f32_e32 v182, v182
	v_rcp_f32_e32 v183, v183
	v_rcp_f32_e32 v184, v184
	v_rcp_f32_e32 v185, v185
	v_rcp_f32_e32 v186, v186
	v_rcp_f32_e32 v187, v187
	v_rcp_f32_e32 v188, v188
	v_rcp_f32_e32 v189, v189
	v_pk_add_f32 v[150:151], v[150:151], s[86:87] op_sel_hi:[1,0] neg_lo:[1,0] neg_hi:[1,0]
	v_pk_add_f32 v[152:153], v[152:153], s[86:87] op_sel_hi:[1,0] neg_lo:[1,0] neg_hi:[1,0]
	v_pk_add_f32 v[154:155], v[154:155], s[86:87] op_sel_hi:[1,0] neg_lo:[1,0] neg_hi:[1,0]
	v_pk_add_f32 v[156:157], v[156:157], s[86:87] op_sel_hi:[1,0] neg_lo:[1,0] neg_hi:[1,0]
	v_pk_mul_f32 v[150:151], v[150:151], v[174:175]
	v_pk_mul_f32 v[152:153], v[152:153], v[176:177]
	v_pk_mul_f32 v[154:155], v[154:155], v[178:179]
	v_pk_mul_f32 v[156:157], v[156:157], v[180:181]
	v_pk_mul_f32 v[182:183], v[114:115], v[182:183]
	v_pk_mul_f32 v[184:185], v[116:117], v[184:185]
	v_pk_mul_f32 v[186:187], v[82:83], v[186:187]
	v_pk_mul_f32 v[188:189], v[84:85], v[188:189]
	v_cvt_pk_bf16_f32 v174, v182, v183
	v_cvt_pk_bf16_f32 v175, v184, v185
	v_cvt_pk_bf16_f32 v176, v186, v187
	v_cvt_pk_bf16_f32 v177, v188, v189
	v_cvt_pk_bf16_f32 v178, v150, v151
	v_cvt_pk_bf16_f32 v179, v152, v153
	v_cvt_pk_bf16_f32 v180, v154, v155
	v_cvt_pk_bf16_f32 v181, v156, v157
	ds_bpermute_b32 v190, v148, v174
	ds_bpermute_b32 v191, v148, v175
	ds_bpermute_b32 v192, v148, v176
	ds_bpermute_b32 v193, v148, v177
	ds_bpermute_b32 v194, v148, v178
	ds_bpermute_b32 v195, v148, v179
	ds_bpermute_b32 v196, v148, v180
	ds_bpermute_b32 v197, v148, v181
	v_pk_mul_f32 v[150:151], v[122:123], s[84:85] op_sel_hi:[1,0]
	v_pk_mul_f32 v[152:153], v[124:125], s[84:85] op_sel_hi:[1,0]
	v_pk_mul_f32 v[154:155], v[90:91], s[84:85] op_sel_hi:[1,0]
	v_pk_mul_f32 v[156:157], v[92:93], s[84:85] op_sel_hi:[1,0]
	v_exp_f32_e32 v150, v150
	v_exp_f32_e32 v151, v151
	v_exp_f32_e32 v152, v152
	v_exp_f32_e32 v153, v153
	v_exp_f32_e32 v154, v154
	v_exp_f32_e32 v155, v155
	v_exp_f32_e32 v156, v156
	v_exp_f32_e32 v157, v157
	v_pk_add_f32 v[150:151], v[150:151], s[86:87] op_sel_hi:[1,0]
	v_pk_add_f32 v[152:153], v[152:153], s[86:87] op_sel_hi:[1,0]
	v_pk_add_f32 v[154:155], v[154:155], s[86:87] op_sel_hi:[1,0]
	v_pk_add_f32 v[156:157], v[156:157], s[86:87] op_sel_hi:[1,0]
	v_rcp_f32_e32 v150, v150
	v_rcp_f32_e32 v151, v151
	v_rcp_f32_e32 v152, v152
	v_rcp_f32_e32 v153, v153
	v_rcp_f32_e32 v154, v154
	v_rcp_f32_e32 v155, v155
	v_rcp_f32_e32 v156, v156
	v_rcp_f32_e32 v157, v157
	v_add_u32_e32 v220, 16, v4
	v_ashrrev_i32_e32 v221, 31, v220
	v_lshlrev_b64 v[222:223], 12, v[220:221]
	v_lshlrev_b64 v[224:225], 11, v[220:221]
	v_lshl_add_u64 v[222:223], v[142:143], 0, v[222:223]
	v_lshl_add_u64 v[224:225], v[144:145], 0, v[224:225]
	s_waitcnt lgkmcnt(0)
	global_store_dwordx4 v[222:223], v[190:193], off nt
	global_store_dwordx4 v[224:225], v[194:197], off nt
	v_pk_add_f32 v[174:175], v[138:139], s[86:87] op_sel_hi:[1,0] neg_lo:[1,0] neg_hi:[1,0]
	v_pk_add_f32 v[176:177], v[140:141], s[86:87] op_sel_hi:[1,0] neg_lo:[1,0] neg_hi:[1,0]
	v_pk_add_f32 v[178:179], v[134:135], s[86:87] op_sel_hi:[1,0] neg_lo:[1,0] neg_hi:[1,0]
	v_pk_add_f32 v[180:181], v[136:137], s[86:87] op_sel_hi:[1,0] neg_lo:[1,0] neg_hi:[1,0]
	v_pk_fma_f32 v[150:151], v[150:151], v[174:175], v[138:139]
	v_pk_fma_f32 v[152:153], v[152:153], v[176:177], v[140:141]
	v_pk_fma_f32 v[154:155], v[154:155], v[178:179], v[134:135]
	v_pk_fma_f32 v[156:157], v[156:157], v[180:181], v[136:137]
	v_log_f32_e32 v158, v150
	v_log_f32_e32 v159, v151
	v_log_f32_e32 v160, v152
	v_log_f32_e32 v161, v153
	v_log_f32_e32 v162, v154
	v_log_f32_e32 v163, v155
	v_log_f32_e32 v164, v156
	v_log_f32_e32 v165, v157
	v_add_f32_dpp v158, v158, v158 row_shr:1 row_mask:0xf bank_mask:0xf bound_ctrl:1
	v_add_f32_dpp v159, v159, v159 row_shr:1 row_mask:0xf bank_mask:0xf bound_ctrl:1
	v_add_f32_dpp v160, v160, v160 row_shr:1 row_mask:0xf bank_mask:0xf bound_ctrl:1
	v_add_f32_dpp v161, v161, v161 row_shr:1 row_mask:0xf bank_mask:0xf bound_ctrl:1
	v_add_f32_dpp v162, v162, v162 row_shr:1 row_mask:0xf bank_mask:0xf bound_ctrl:1
	v_add_f32_dpp v163, v163, v163 row_shr:1 row_mask:0xf bank_mask:0xf bound_ctrl:1
	v_add_f32_dpp v164, v164, v164 row_shr:1 row_mask:0xf bank_mask:0xf bound_ctrl:1
	v_add_f32_dpp v165, v165, v165 row_shr:1 row_mask:0xf bank_mask:0xf bound_ctrl:1
	v_add_f32_dpp v158, v158, v158 row_shr:2 row_mask:0xf bank_mask:0xf bound_ctrl:1
	v_add_f32_dpp v159, v159, v159 row_shr:2 row_mask:0xf bank_mask:0xf bound_ctrl:1
	v_add_f32_dpp v160, v160, v160 row_shr:2 row_mask:0xf bank_mask:0xf bound_ctrl:1
	v_add_f32_dpp v161, v161, v161 row_shr:2 row_mask:0xf bank_mask:0xf bound_ctrl:1
	v_add_f32_dpp v162, v162, v162 row_shr:2 row_mask:0xf bank_mask:0xf bound_ctrl:1
	v_add_f32_dpp v163, v163, v163 row_shr:2 row_mask:0xf bank_mask:0xf bound_ctrl:1
	v_add_f32_dpp v164, v164, v164 row_shr:2 row_mask:0xf bank_mask:0xf bound_ctrl:1
	v_add_f32_dpp v165, v165, v165 row_shr:2 row_mask:0xf bank_mask:0xf bound_ctrl:1
	v_add_f32_dpp v158, v158, v158 row_shr:4 row_mask:0xf bank_mask:0xf bound_ctrl:1
	v_add_f32_dpp v159, v159, v159 row_shr:4 row_mask:0xf bank_mask:0xf bound_ctrl:1
	v_add_f32_dpp v160, v160, v160 row_shr:4 row_mask:0xf bank_mask:0xf bound_ctrl:1
	v_add_f32_dpp v161, v161, v161 row_shr:4 row_mask:0xf bank_mask:0xf bound_ctrl:1
	v_add_f32_dpp v162, v162, v162 row_shr:4 row_mask:0xf bank_mask:0xf bound_ctrl:1
	v_add_f32_dpp v163, v163, v163 row_shr:4 row_mask:0xf bank_mask:0xf bound_ctrl:1
	v_add_f32_dpp v164, v164, v164 row_shr:4 row_mask:0xf bank_mask:0xf bound_ctrl:1
	v_add_f32_dpp v165, v165, v165 row_shr:4 row_mask:0xf bank_mask:0xf bound_ctrl:1
	v_add_f32_dpp v158, v158, v158 row_shr:8 row_mask:0xf bank_mask:0xf bound_ctrl:1
	v_add_f32_dpp v159, v159, v159 row_shr:8 row_mask:0xf bank_mask:0xf bound_ctrl:1
	v_add_f32_dpp v160, v160, v160 row_shr:8 row_mask:0xf bank_mask:0xf bound_ctrl:1
	v_add_f32_dpp v161, v161, v161 row_shr:8 row_mask:0xf bank_mask:0xf bound_ctrl:1
	v_add_f32_dpp v162, v162, v162 row_shr:8 row_mask:0xf bank_mask:0xf bound_ctrl:1
	v_add_f32_dpp v163, v163, v163 row_shr:8 row_mask:0xf bank_mask:0xf bound_ctrl:1
	v_add_f32_dpp v164, v164, v164 row_shr:8 row_mask:0xf bank_mask:0xf bound_ctrl:1
	v_add_f32_dpp v165, v165, v165 row_shr:8 row_mask:0xf bank_mask:0xf bound_ctrl:1
	v_add_f32_dpp v158, v166, v158 row_newbcast:15 row_mask:0xf bank_mask:0xf bound_ctrl:1
	v_add_f32_dpp v159, v167, v159 row_newbcast:15 row_mask:0xf bank_mask:0xf bound_ctrl:1
	v_add_f32_dpp v160, v168, v160 row_newbcast:15 row_mask:0xf bank_mask:0xf bound_ctrl:1
	v_add_f32_dpp v161, v169, v161 row_newbcast:15 row_mask:0xf bank_mask:0xf bound_ctrl:1
	v_add_f32_dpp v162, v170, v162 row_newbcast:15 row_mask:0xf bank_mask:0xf bound_ctrl:1
	v_add_f32_dpp v163, v171, v163 row_newbcast:15 row_mask:0xf bank_mask:0xf bound_ctrl:1
	v_add_f32_dpp v164, v172, v164 row_newbcast:15 row_mask:0xf bank_mask:0xf bound_ctrl:1
	v_add_f32_dpp v165, v173, v165 row_newbcast:15 row_mask:0xf bank_mask:0xf bound_ctrl:1
	v_exp_f32_e64 v174, -v158
	v_exp_f32_e64 v175, -v159
	v_exp_f32_e64 v176, -v160
	v_exp_f32_e64 v177, -v161
	v_exp_f32_e64 v178, -v162
	v_exp_f32_e64 v179, -v163
	v_exp_f32_e64 v180, -v164
	v_exp_f32_e64 v181, -v165
	v_pk_mul_f32 v[182:183], v[110:111], s[84:85] op_sel_hi:[1,0]
	v_pk_mul_f32 v[184:185], v[112:113], s[84:85] op_sel_hi:[1,0]
	v_pk_mul_f32 v[186:187], v[78:79], s[84:85] op_sel_hi:[1,0]
	v_pk_mul_f32 v[188:189], v[80:81], s[84:85] op_sel_hi:[1,0]
	v_exp_f32_e32 v182, v182
	v_exp_f32_e32 v183, v183
	v_exp_f32_e32 v184, v184
	v_exp_f32_e32 v185, v185
	v_exp_f32_e32 v186, v186
	v_exp_f32_e32 v187, v187
	v_exp_f32_e32 v188, v188
	v_exp_f32_e32 v189, v189
	v_pk_add_f32 v[182:183], v[182:183], s[86:87] op_sel_hi:[1,0]
	v_pk_add_f32 v[184:185], v[184:185], s[86:87] op_sel_hi:[1,0]
	v_pk_add_f32 v[186:187], v[186:187], s[86:87] op_sel_hi:[1,0]
	v_pk_add_f32 v[188:189], v[188:189], s[86:87] op_sel_hi:[1,0]
	v_pk_mul_f32 v[182:183], v[182:183], v[174:175]
	v_pk_mul_f32 v[184:185], v[184:185], v[176:177]
	v_pk_mul_f32 v[186:187], v[186:187], v[178:179]
	v_pk_mul_f32 v[188:189], v[188:189], v[180:181]
	v_rcp_f32_e32 v182, v182
	v_rcp_f32_e32 v183, v183
	v_rcp_f32_e32 v184, v184
	v_rcp_f32_e32 v185, v185
	v_rcp_f32_e32 v186, v186
	v_rcp_f32_e32 v187, v187
	v_rcp_f32_e32 v188, v188
	v_rcp_f32_e32 v189, v189
	v_pk_add_f32 v[150:151], v[150:151], s[86:87] op_sel_hi:[1,0] neg_lo:[1,0] neg_hi:[1,0]
	v_pk_add_f32 v[152:153], v[152:153], s[86:87] op_sel_hi:[1,0] neg_lo:[1,0] neg_hi:[1,0]
	v_pk_add_f32 v[154:155], v[154:155], s[86:87] op_sel_hi:[1,0] neg_lo:[1,0] neg_hi:[1,0]
	v_pk_add_f32 v[156:157], v[156:157], s[86:87] op_sel_hi:[1,0] neg_lo:[1,0] neg_hi:[1,0]
	v_pk_mul_f32 v[150:151], v[150:151], v[174:175]
	v_pk_mul_f32 v[152:153], v[152:153], v[176:177]
	v_pk_mul_f32 v[154:155], v[154:155], v[178:179]
	v_pk_mul_f32 v[156:157], v[156:157], v[180:181]
	v_pk_mul_f32 v[182:183], v[110:111], v[182:183]
	v_pk_mul_f32 v[184:185], v[112:113], v[184:185]
	v_pk_mul_f32 v[186:187], v[78:79], v[186:187]
	v_pk_mul_f32 v[188:189], v[80:81], v[188:189]
	v_cvt_pk_bf16_f32 v174, v182, v183
	v_cvt_pk_bf16_f32 v175, v184, v185
	v_cvt_pk_bf16_f32 v176, v186, v187
	v_cvt_pk_bf16_f32 v177, v188, v189
	v_cvt_pk_bf16_f32 v178, v150, v151
	v_cvt_pk_bf16_f32 v179, v152, v153
	v_cvt_pk_bf16_f32 v180, v154, v155
	v_cvt_pk_bf16_f32 v181, v156, v157
	ds_bpermute_b32 v190, v148, v174
	ds_bpermute_b32 v191, v148, v175
	ds_bpermute_b32 v192, v148, v176
	ds_bpermute_b32 v193, v148, v177
	ds_bpermute_b32 v194, v148, v178
	ds_bpermute_b32 v195, v148, v179
	ds_bpermute_b32 v196, v148, v180
	ds_bpermute_b32 v197, v148, v181
	v_pk_mul_f32 v[150:151], v[118:119], s[84:85] op_sel_hi:[1,0]
	v_pk_mul_f32 v[152:153], v[120:121], s[84:85] op_sel_hi:[1,0]
	v_pk_mul_f32 v[154:155], v[86:87], s[84:85] op_sel_hi:[1,0]
	v_pk_mul_f32 v[156:157], v[88:89], s[84:85] op_sel_hi:[1,0]
	v_exp_f32_e32 v150, v150
	v_exp_f32_e32 v151, v151
	v_exp_f32_e32 v152, v152
	v_exp_f32_e32 v153, v153
	v_exp_f32_e32 v154, v154
	v_exp_f32_e32 v155, v155
	v_exp_f32_e32 v156, v156
	v_exp_f32_e32 v157, v157
	v_pk_add_f32 v[150:151], v[150:151], s[86:87] op_sel_hi:[1,0]
	v_pk_add_f32 v[152:153], v[152:153], s[86:87] op_sel_hi:[1,0]
	v_pk_add_f32 v[154:155], v[154:155], s[86:87] op_sel_hi:[1,0]
	v_pk_add_f32 v[156:157], v[156:157], s[86:87] op_sel_hi:[1,0]
	v_rcp_f32_e32 v150, v150
	v_rcp_f32_e32 v151, v151
	v_rcp_f32_e32 v152, v152
	v_rcp_f32_e32 v153, v153
	v_rcp_f32_e32 v154, v154
	v_rcp_f32_e32 v155, v155
	v_rcp_f32_e32 v156, v156
	v_rcp_f32_e32 v157, v157
	v_add_u32_e32 v220, 32, v4
	v_ashrrev_i32_e32 v221, 31, v220
	v_lshlrev_b64 v[222:223], 12, v[220:221]
	v_lshlrev_b64 v[224:225], 11, v[220:221]
	v_lshl_add_u64 v[222:223], v[142:143], 0, v[222:223]
	v_lshl_add_u64 v[224:225], v[144:145], 0, v[224:225]
	s_waitcnt lgkmcnt(0)
	global_store_dwordx4 v[222:223], v[190:193], off nt
	global_store_dwordx4 v[224:225], v[194:197], off nt
	v_pk_add_f32 v[174:175], v[138:139], s[86:87] op_sel_hi:[1,0] neg_lo:[1,0] neg_hi:[1,0]
	v_pk_add_f32 v[176:177], v[140:141], s[86:87] op_sel_hi:[1,0] neg_lo:[1,0] neg_hi:[1,0]
	v_pk_add_f32 v[178:179], v[134:135], s[86:87] op_sel_hi:[1,0] neg_lo:[1,0] neg_hi:[1,0]
	v_pk_add_f32 v[180:181], v[136:137], s[86:87] op_sel_hi:[1,0] neg_lo:[1,0] neg_hi:[1,0]
	v_pk_fma_f32 v[150:151], v[150:151], v[174:175], v[138:139]
	v_pk_fma_f32 v[152:153], v[152:153], v[176:177], v[140:141]
	v_pk_fma_f32 v[154:155], v[154:155], v[178:179], v[134:135]
	v_pk_fma_f32 v[156:157], v[156:157], v[180:181], v[136:137]
	v_log_f32_e32 v166, v150
	v_log_f32_e32 v167, v151
	v_log_f32_e32 v168, v152
	v_log_f32_e32 v169, v153
	v_log_f32_e32 v170, v154
	v_log_f32_e32 v171, v155
	v_log_f32_e32 v172, v156
	v_log_f32_e32 v173, v157
	v_add_f32_dpp v166, v166, v166 row_shr:1 row_mask:0xf bank_mask:0xf bound_ctrl:1
	v_add_f32_dpp v167, v167, v167 row_shr:1 row_mask:0xf bank_mask:0xf bound_ctrl:1
	v_add_f32_dpp v168, v168, v168 row_shr:1 row_mask:0xf bank_mask:0xf bound_ctrl:1
	v_add_f32_dpp v169, v169, v169 row_shr:1 row_mask:0xf bank_mask:0xf bound_ctrl:1
	v_add_f32_dpp v170, v170, v170 row_shr:1 row_mask:0xf bank_mask:0xf bound_ctrl:1
	v_add_f32_dpp v171, v171, v171 row_shr:1 row_mask:0xf bank_mask:0xf bound_ctrl:1
	v_add_f32_dpp v172, v172, v172 row_shr:1 row_mask:0xf bank_mask:0xf bound_ctrl:1
	v_add_f32_dpp v173, v173, v173 row_shr:1 row_mask:0xf bank_mask:0xf bound_ctrl:1
	v_add_f32_dpp v166, v166, v166 row_shr:2 row_mask:0xf bank_mask:0xf bound_ctrl:1
	v_add_f32_dpp v167, v167, v167 row_shr:2 row_mask:0xf bank_mask:0xf bound_ctrl:1
	v_add_f32_dpp v168, v168, v168 row_shr:2 row_mask:0xf bank_mask:0xf bound_ctrl:1
	v_add_f32_dpp v169, v169, v169 row_shr:2 row_mask:0xf bank_mask:0xf bound_ctrl:1
	v_add_f32_dpp v170, v170, v170 row_shr:2 row_mask:0xf bank_mask:0xf bound_ctrl:1
	v_add_f32_dpp v171, v171, v171 row_shr:2 row_mask:0xf bank_mask:0xf bound_ctrl:1
	v_add_f32_dpp v172, v172, v172 row_shr:2 row_mask:0xf bank_mask:0xf bound_ctrl:1
	v_add_f32_dpp v173, v173, v173 row_shr:2 row_mask:0xf bank_mask:0xf bound_ctrl:1
	v_add_f32_dpp v166, v166, v166 row_shr:4 row_mask:0xf bank_mask:0xf bound_ctrl:1
	v_add_f32_dpp v167, v167, v167 row_shr:4 row_mask:0xf bank_mask:0xf bound_ctrl:1
	v_add_f32_dpp v168, v168, v168 row_shr:4 row_mask:0xf bank_mask:0xf bound_ctrl:1
	v_add_f32_dpp v169, v169, v169 row_shr:4 row_mask:0xf bank_mask:0xf bound_ctrl:1
	v_add_f32_dpp v170, v170, v170 row_shr:4 row_mask:0xf bank_mask:0xf bound_ctrl:1
	v_add_f32_dpp v171, v171, v171 row_shr:4 row_mask:0xf bank_mask:0xf bound_ctrl:1
	v_add_f32_dpp v172, v172, v172 row_shr:4 row_mask:0xf bank_mask:0xf bound_ctrl:1
	v_add_f32_dpp v173, v173, v173 row_shr:4 row_mask:0xf bank_mask:0xf bound_ctrl:1
	v_add_f32_dpp v166, v166, v166 row_shr:8 row_mask:0xf bank_mask:0xf bound_ctrl:1
	v_add_f32_dpp v167, v167, v167 row_shr:8 row_mask:0xf bank_mask:0xf bound_ctrl:1
	v_add_f32_dpp v168, v168, v168 row_shr:8 row_mask:0xf bank_mask:0xf bound_ctrl:1
	v_add_f32_dpp v169, v169, v169 row_shr:8 row_mask:0xf bank_mask:0xf bound_ctrl:1
	v_add_f32_dpp v170, v170, v170 row_shr:8 row_mask:0xf bank_mask:0xf bound_ctrl:1
	v_add_f32_dpp v171, v171, v171 row_shr:8 row_mask:0xf bank_mask:0xf bound_ctrl:1
	v_add_f32_dpp v172, v172, v172 row_shr:8 row_mask:0xf bank_mask:0xf bound_ctrl:1
	v_add_f32_dpp v173, v173, v173 row_shr:8 row_mask:0xf bank_mask:0xf bound_ctrl:1
	v_add_f32_dpp v166, v158, v166 row_newbcast:15 row_mask:0xf bank_mask:0xf bound_ctrl:1
	v_add_f32_dpp v167, v159, v167 row_newbcast:15 row_mask:0xf bank_mask:0xf bound_ctrl:1
	v_add_f32_dpp v168, v160, v168 row_newbcast:15 row_mask:0xf bank_mask:0xf bound_ctrl:1
	v_add_f32_dpp v169, v161, v169 row_newbcast:15 row_mask:0xf bank_mask:0xf bound_ctrl:1
	v_add_f32_dpp v170, v162, v170 row_newbcast:15 row_mask:0xf bank_mask:0xf bound_ctrl:1
	v_add_f32_dpp v171, v163, v171 row_newbcast:15 row_mask:0xf bank_mask:0xf bound_ctrl:1
	v_add_f32_dpp v172, v164, v172 row_newbcast:15 row_mask:0xf bank_mask:0xf bound_ctrl:1
	v_add_f32_dpp v173, v165, v173 row_newbcast:15 row_mask:0xf bank_mask:0xf bound_ctrl:1
	v_exp_f32_e64 v174, -v166
	v_exp_f32_e64 v175, -v167
	v_exp_f32_e64 v176, -v168
	v_exp_f32_e64 v177, -v169
	v_exp_f32_e64 v178, -v170
	v_exp_f32_e64 v179, -v171
	v_exp_f32_e64 v180, -v172
	v_exp_f32_e64 v181, -v173
	v_pk_mul_f32 v[182:183], v[106:107], s[84:85] op_sel_hi:[1,0]
	v_pk_mul_f32 v[184:185], v[108:109], s[84:85] op_sel_hi:[1,0]
	v_pk_mul_f32 v[186:187], v[74:75], s[84:85] op_sel_hi:[1,0]
	v_pk_mul_f32 v[188:189], v[76:77], s[84:85] op_sel_hi:[1,0]
	v_exp_f32_e32 v182, v182
	v_exp_f32_e32 v183, v183
	v_exp_f32_e32 v184, v184
	v_exp_f32_e32 v185, v185
	v_exp_f32_e32 v186, v186
	v_exp_f32_e32 v187, v187
	v_exp_f32_e32 v188, v188
	v_exp_f32_e32 v189, v189
	v_pk_add_f32 v[182:183], v[182:183], s[86:87] op_sel_hi:[1,0]
	v_pk_add_f32 v[184:185], v[184:185], s[86:87] op_sel_hi:[1,0]
	v_pk_add_f32 v[186:187], v[186:187], s[86:87] op_sel_hi:[1,0]
	v_pk_add_f32 v[188:189], v[188:189], s[86:87] op_sel_hi:[1,0]
	v_pk_mul_f32 v[182:183], v[182:183], v[174:175]
	v_pk_mul_f32 v[184:185], v[184:185], v[176:177]
	v_pk_mul_f32 v[186:187], v[186:187], v[178:179]
	v_pk_mul_f32 v[188:189], v[188:189], v[180:181]
	v_rcp_f32_e32 v182, v182
	v_rcp_f32_e32 v183, v183
	v_rcp_f32_e32 v184, v184
	v_rcp_f32_e32 v185, v185
	v_rcp_f32_e32 v186, v186
	v_rcp_f32_e32 v187, v187
	v_rcp_f32_e32 v188, v188
	v_rcp_f32_e32 v189, v189
	v_pk_add_f32 v[150:151], v[150:151], s[86:87] op_sel_hi:[1,0] neg_lo:[1,0] neg_hi:[1,0]
	v_pk_add_f32 v[152:153], v[152:153], s[86:87] op_sel_hi:[1,0] neg_lo:[1,0] neg_hi:[1,0]
	v_pk_add_f32 v[154:155], v[154:155], s[86:87] op_sel_hi:[1,0] neg_lo:[1,0] neg_hi:[1,0]
	v_pk_add_f32 v[156:157], v[156:157], s[86:87] op_sel_hi:[1,0] neg_lo:[1,0] neg_hi:[1,0]
	v_pk_mul_f32 v[150:151], v[150:151], v[174:175]
	v_pk_mul_f32 v[152:153], v[152:153], v[176:177]
	v_pk_mul_f32 v[154:155], v[154:155], v[178:179]
	v_pk_mul_f32 v[156:157], v[156:157], v[180:181]
	v_pk_mul_f32 v[182:183], v[106:107], v[182:183]
	v_pk_mul_f32 v[184:185], v[108:109], v[184:185]
	v_pk_mul_f32 v[186:187], v[74:75], v[186:187]
	v_pk_mul_f32 v[188:189], v[76:77], v[188:189]
	v_cvt_pk_bf16_f32 v174, v182, v183
	v_cvt_pk_bf16_f32 v175, v184, v185
	v_cvt_pk_bf16_f32 v176, v186, v187
	v_cvt_pk_bf16_f32 v177, v188, v189
	v_cvt_pk_bf16_f32 v178, v150, v151
	v_cvt_pk_bf16_f32 v179, v152, v153
	v_cvt_pk_bf16_f32 v180, v154, v155
	v_cvt_pk_bf16_f32 v181, v156, v157
	ds_bpermute_b32 v190, v148, v174
	ds_bpermute_b32 v191, v148, v175
	ds_bpermute_b32 v192, v148, v176
	ds_bpermute_b32 v193, v148, v177
	ds_bpermute_b32 v194, v148, v178
	ds_bpermute_b32 v195, v148, v179
	ds_bpermute_b32 v196, v148, v180
	ds_bpermute_b32 v197, v148, v181
	v_add_u32_e32 v220, 48, v4
	v_ashrrev_i32_e32 v221, 31, v220
	v_lshlrev_b64 v[222:223], 12, v[220:221]
	v_lshlrev_b64 v[224:225], 11, v[220:221]
	v_lshl_add_u64 v[222:223], v[142:143], 0, v[222:223]
	v_lshl_add_u64 v[224:225], v[144:145], 0, v[224:225]
	s_waitcnt lgkmcnt(0)
	global_store_dwordx4 v[222:223], v[190:193], off nt
	global_store_dwordx4 v[224:225], v[194:197], off nt
	s_and_saveexec_b64 s[0:1], s[90:91]
	s_ashr_i32 s2, s43, 6
	s_ashr_i32 s3, s2, 31
	s_lshl_b64 s[2:3], s[2:3], 12
	v_lshl_add_u64 v[222:223], v[146:147], 0, s[2:3]
	global_store_dwordx4 v[222:223], v[166:169], off
	global_store_dwordx4 v[222:223], v[170:173], off offset:16
	s_or_b64 exec, exec, s[0:1]
	s_addk_i32 s43, 0x80
	v_add_u32_e32 v4, s43, v149
	v_pk_mul_f32 v[150:151], v[62:63], s[84:85] op_sel_hi:[1,0]
	v_pk_mul_f32 v[152:153], v[64:65], s[84:85] op_sel_hi:[1,0]
	v_pk_mul_f32 v[154:155], v[30:31], s[84:85] op_sel_hi:[1,0]
	v_pk_mul_f32 v[156:157], v[32:33], s[84:85] op_sel_hi:[1,0]
	v_exp_f32_e32 v150, v150
	v_exp_f32_e32 v151, v151
	v_exp_f32_e32 v152, v152
	v_exp_f32_e32 v153, v153
	v_exp_f32_e32 v154, v154
	v_exp_f32_e32 v155, v155
	v_exp_f32_e32 v156, v156
	v_exp_f32_e32 v157, v157
	v_pk_add_f32 v[150:151], v[150:151], s[86:87] op_sel_hi:[1,0]
	v_pk_add_f32 v[152:153], v[152:153], s[86:87] op_sel_hi:[1,0]
	v_pk_add_f32 v[154:155], v[154:155], s[86:87] op_sel_hi:[1,0]
	v_pk_add_f32 v[156:157], v[156:157], s[86:87] op_sel_hi:[1,0]
	v_rcp_f32_e32 v150, v150
	v_rcp_f32_e32 v151, v151
	v_rcp_f32_e32 v152, v152
	v_rcp_f32_e32 v153, v153
	v_rcp_f32_e32 v154, v154
	v_rcp_f32_e32 v155, v155
	v_rcp_f32_e32 v156, v156
	v_rcp_f32_e32 v157, v157
	v_pk_add_f32 v[174:175], v[138:139], s[86:87] op_sel_hi:[1,0] neg_lo:[1,0] neg_hi:[1,0]
	v_pk_add_f32 v[176:177], v[140:141], s[86:87] op_sel_hi:[1,0] neg_lo:[1,0] neg_hi:[1,0]
	v_pk_add_f32 v[178:179], v[134:135], s[86:87] op_sel_hi:[1,0] neg_lo:[1,0] neg_hi:[1,0]
	v_pk_add_f32 v[180:181], v[136:137], s[86:87] op_sel_hi:[1,0] neg_lo:[1,0] neg_hi:[1,0]
	v_pk_fma_f32 v[150:151], v[150:151], v[174:175], v[138:139]
	v_pk_fma_f32 v[152:153], v[152:153], v[176:177], v[140:141]
	v_pk_fma_f32 v[154:155], v[154:155], v[178:179], v[134:135]
	v_pk_fma_f32 v[156:157], v[156:157], v[180:181], v[136:137]
	v_log_f32_e32 v158, v150
	v_log_f32_e32 v159, v151
	v_log_f32_e32 v160, v152
	v_log_f32_e32 v161, v153
	v_log_f32_e32 v162, v154
	v_log_f32_e32 v163, v155
	v_log_f32_e32 v164, v156
	v_log_f32_e32 v165, v157
	v_add_f32_dpp v158, v158, v158 row_shr:1 row_mask:0xf bank_mask:0xf bound_ctrl:1
	v_add_f32_dpp v159, v159, v159 row_shr:1 row_mask:0xf bank_mask:0xf bound_ctrl:1
	v_add_f32_dpp v160, v160, v160 row_shr:1 row_mask:0xf bank_mask:0xf bound_ctrl:1
	v_add_f32_dpp v161, v161, v161 row_shr:1 row_mask:0xf bank_mask:0xf bound_ctrl:1
	v_add_f32_dpp v162, v162, v162 row_shr:1 row_mask:0xf bank_mask:0xf bound_ctrl:1
	v_add_f32_dpp v163, v163, v163 row_shr:1 row_mask:0xf bank_mask:0xf bound_ctrl:1
	v_add_f32_dpp v164, v164, v164 row_shr:1 row_mask:0xf bank_mask:0xf bound_ctrl:1
	v_add_f32_dpp v165, v165, v165 row_shr:1 row_mask:0xf bank_mask:0xf bound_ctrl:1
	v_add_f32_dpp v158, v158, v158 row_shr:2 row_mask:0xf bank_mask:0xf bound_ctrl:1
	v_add_f32_dpp v159, v159, v159 row_shr:2 row_mask:0xf bank_mask:0xf bound_ctrl:1
	v_add_f32_dpp v160, v160, v160 row_shr:2 row_mask:0xf bank_mask:0xf bound_ctrl:1
	v_add_f32_dpp v161, v161, v161 row_shr:2 row_mask:0xf bank_mask:0xf bound_ctrl:1
	v_add_f32_dpp v162, v162, v162 row_shr:2 row_mask:0xf bank_mask:0xf bound_ctrl:1
	v_add_f32_dpp v163, v163, v163 row_shr:2 row_mask:0xf bank_mask:0xf bound_ctrl:1
	v_add_f32_dpp v164, v164, v164 row_shr:2 row_mask:0xf bank_mask:0xf bound_ctrl:1
	v_add_f32_dpp v165, v165, v165 row_shr:2 row_mask:0xf bank_mask:0xf bound_ctrl:1
	v_add_f32_dpp v158, v158, v158 row_shr:4 row_mask:0xf bank_mask:0xf bound_ctrl:1
	v_add_f32_dpp v159, v159, v159 row_shr:4 row_mask:0xf bank_mask:0xf bound_ctrl:1
	v_add_f32_dpp v160, v160, v160 row_shr:4 row_mask:0xf bank_mask:0xf bound_ctrl:1
	v_add_f32_dpp v161, v161, v161 row_shr:4 row_mask:0xf bank_mask:0xf bound_ctrl:1
	v_add_f32_dpp v162, v162, v162 row_shr:4 row_mask:0xf bank_mask:0xf bound_ctrl:1
	v_add_f32_dpp v163, v163, v163 row_shr:4 row_mask:0xf bank_mask:0xf bound_ctrl:1
	v_add_f32_dpp v164, v164, v164 row_shr:4 row_mask:0xf bank_mask:0xf bound_ctrl:1
	v_add_f32_dpp v165, v165, v165 row_shr:4 row_mask:0xf bank_mask:0xf bound_ctrl:1
	v_add_f32_dpp v158, v158, v158 row_shr:8 row_mask:0xf bank_mask:0xf bound_ctrl:1
	v_add_f32_dpp v159, v159, v159 row_shr:8 row_mask:0xf bank_mask:0xf bound_ctrl:1
	v_add_f32_dpp v160, v160, v160 row_shr:8 row_mask:0xf bank_mask:0xf bound_ctrl:1
	v_add_f32_dpp v161, v161, v161 row_shr:8 row_mask:0xf bank_mask:0xf bound_ctrl:1
	v_add_f32_dpp v162, v162, v162 row_shr:8 row_mask:0xf bank_mask:0xf bound_ctrl:1
	v_add_f32_dpp v163, v163, v163 row_shr:8 row_mask:0xf bank_mask:0xf bound_ctrl:1
	v_add_f32_dpp v164, v164, v164 row_shr:8 row_mask:0xf bank_mask:0xf bound_ctrl:1
	v_add_f32_dpp v165, v165, v165 row_shr:8 row_mask:0xf bank_mask:0xf bound_ctrl:1
	v_exp_f32_e64 v174, -v158
	v_exp_f32_e64 v175, -v159
	v_exp_f32_e64 v176, -v160
	v_exp_f32_e64 v177, -v161
	v_exp_f32_e64 v178, -v162
	v_exp_f32_e64 v179, -v163
	v_exp_f32_e64 v180, -v164
	v_exp_f32_e64 v181, -v165
	v_pk_mul_f32 v[182:183], v[38:39], s[84:85] op_sel_hi:[1,0]
	v_pk_mul_f32 v[184:185], v[40:41], s[84:85] op_sel_hi:[1,0]
	v_pk_mul_f32 v[186:187], v[6:7], s[84:85] op_sel_hi:[1,0]
	v_pk_mul_f32 v[188:189], v[8:9], s[84:85] op_sel_hi:[1,0]
	v_exp_f32_e32 v182, v182
	v_exp_f32_e32 v183, v183
	v_exp_f32_e32 v184, v184
	v_exp_f32_e32 v185, v185
	v_exp_f32_e32 v186, v186
	v_exp_f32_e32 v187, v187
	v_exp_f32_e32 v188, v188
	v_exp_f32_e32 v189, v189
	v_pk_add_f32 v[182:183], v[182:183], s[86:87] op_sel_hi:[1,0]
	v_pk_add_f32 v[184:185], v[184:185], s[86:87] op_sel_hi:[1,0]
	v_pk_add_f32 v[186:187], v[186:187], s[86:87] op_sel_hi:[1,0]
	v_pk_add_f32 v[188:189], v[188:189], s[86:87] op_sel_hi:[1,0]
	v_pk_mul_f32 v[182:183], v[182:183], v[174:175]
	v_pk_mul_f32 v[184:185], v[184:185], v[176:177]
	v_pk_mul_f32 v[186:187], v[186:187], v[178:179]
	v_pk_mul_f32 v[188:189], v[188:189], v[180:181]
	v_rcp_f32_e32 v182, v182
	v_rcp_f32_e32 v183, v183
	v_rcp_f32_e32 v184, v184
	v_rcp_f32_e32 v185, v185
	v_rcp_f32_e32 v186, v186
	v_rcp_f32_e32 v187, v187
	v_rcp_f32_e32 v188, v188
	v_rcp_f32_e32 v189, v189
	v_pk_add_f32 v[150:151], v[150:151], s[86:87] op_sel_hi:[1,0] neg_lo:[1,0] neg_hi:[1,0]
	v_pk_add_f32 v[152:153], v[152:153], s[86:87] op_sel_hi:[1,0] neg_lo:[1,0] neg_hi:[1,0]
	v_pk_add_f32 v[154:155], v[154:155], s[86:87] op_sel_hi:[1,0] neg_lo:[1,0] neg_hi:[1,0]
	v_pk_add_f32 v[156:157], v[156:157], s[86:87] op_sel_hi:[1,0] neg_lo:[1,0] neg_hi:[1,0]
	v_pk_mul_f32 v[150:151], v[150:151], v[174:175]
	v_pk_mul_f32 v[152:153], v[152:153], v[176:177]
	v_pk_mul_f32 v[154:155], v[154:155], v[178:179]
	v_pk_mul_f32 v[156:157], v[156:157], v[180:181]
	v_pk_mul_f32 v[182:183], v[38:39], v[182:183]
	v_pk_mul_f32 v[184:185], v[40:41], v[184:185]
	v_pk_mul_f32 v[186:187], v[6:7], v[186:187]
	v_pk_mul_f32 v[188:189], v[8:9], v[188:189]
	v_cvt_pk_bf16_f32 v174, v182, v183
	v_cvt_pk_bf16_f32 v175, v184, v185
	v_cvt_pk_bf16_f32 v176, v186, v187
	v_cvt_pk_bf16_f32 v177, v188, v189
	v_cvt_pk_bf16_f32 v178, v150, v151
	v_cvt_pk_bf16_f32 v179, v152, v153
	v_cvt_pk_bf16_f32 v180, v154, v155
	v_cvt_pk_bf16_f32 v181, v156, v157
	ds_bpermute_b32 v190, v148, v174
	ds_bpermute_b32 v191, v148, v175
	ds_bpermute_b32 v192, v148, v176
	ds_bpermute_b32 v193, v148, v177
	ds_bpermute_b32 v194, v148, v178
	ds_bpermute_b32 v195, v148, v179
	ds_bpermute_b32 v196, v148, v180
	ds_bpermute_b32 v197, v148, v181
	v_pk_mul_f32 v[150:151], v[66:67], s[84:85] op_sel_hi:[1,0]
	v_pk_mul_f32 v[152:153], v[68:69], s[84:85] op_sel_hi:[1,0]
	v_pk_mul_f32 v[154:155], v[34:35], s[84:85] op_sel_hi:[1,0]
	v_pk_mul_f32 v[156:157], v[36:37], s[84:85] op_sel_hi:[1,0]
	v_exp_f32_e32 v150, v150
	v_exp_f32_e32 v151, v151
	v_exp_f32_e32 v152, v152
	v_exp_f32_e32 v153, v153
	v_exp_f32_e32 v154, v154
	v_exp_f32_e32 v155, v155
	v_exp_f32_e32 v156, v156
	v_exp_f32_e32 v157, v157
	v_pk_add_f32 v[150:151], v[150:151], s[86:87] op_sel_hi:[1,0]
	v_pk_add_f32 v[152:153], v[152:153], s[86:87] op_sel_hi:[1,0]
	v_pk_add_f32 v[154:155], v[154:155], s[86:87] op_sel_hi:[1,0]
	v_pk_add_f32 v[156:157], v[156:157], s[86:87] op_sel_hi:[1,0]
	v_rcp_f32_e32 v150, v150
	v_rcp_f32_e32 v151, v151
	v_rcp_f32_e32 v152, v152
	v_rcp_f32_e32 v153, v153
	v_rcp_f32_e32 v154, v154
	v_rcp_f32_e32 v155, v155
	v_rcp_f32_e32 v156, v156
	v_rcp_f32_e32 v157, v157
	v_mov_b32_e32 v220, v4
	v_ashrrev_i32_e32 v221, 31, v220
	v_lshlrev_b64 v[222:223], 12, v[220:221]
	v_lshlrev_b64 v[224:225], 11, v[220:221]
	v_lshl_add_u64 v[222:223], v[142:143], 0, v[222:223]
	v_lshl_add_u64 v[224:225], v[144:145], 0, v[224:225]
	s_waitcnt lgkmcnt(0)
	global_store_dwordx4 v[222:223], v[190:193], off nt
	global_store_dwordx4 v[224:225], v[194:197], off nt
	v_pk_add_f32 v[174:175], v[138:139], s[86:87] op_sel_hi:[1,0] neg_lo:[1,0] neg_hi:[1,0]
	v_pk_add_f32 v[176:177], v[140:141], s[86:87] op_sel_hi:[1,0] neg_lo:[1,0] neg_hi:[1,0]
	v_pk_add_f32 v[178:179], v[134:135], s[86:87] op_sel_hi:[1,0] neg_lo:[1,0] neg_hi:[1,0]
	v_pk_add_f32 v[180:181], v[136:137], s[86:87] op_sel_hi:[1,0] neg_lo:[1,0] neg_hi:[1,0]
	v_pk_fma_f32 v[150:151], v[150:151], v[174:175], v[138:139]
	v_pk_fma_f32 v[152:153], v[152:153], v[176:177], v[140:141]
	v_pk_fma_f32 v[154:155], v[154:155], v[178:179], v[134:135]
	v_pk_fma_f32 v[156:157], v[156:157], v[180:181], v[136:137]
	v_log_f32_e32 v166, v150
	v_log_f32_e32 v167, v151
	v_log_f32_e32 v168, v152
	v_log_f32_e32 v169, v153
	v_log_f32_e32 v170, v154
	v_log_f32_e32 v171, v155
	v_log_f32_e32 v172, v156
	v_log_f32_e32 v173, v157
	v_add_f32_dpp v166, v166, v166 row_shr:1 row_mask:0xf bank_mask:0xf bound_ctrl:1
	v_add_f32_dpp v167, v167, v167 row_shr:1 row_mask:0xf bank_mask:0xf bound_ctrl:1
	v_add_f32_dpp v168, v168, v168 row_shr:1 row_mask:0xf bank_mask:0xf bound_ctrl:1
	v_add_f32_dpp v169, v169, v169 row_shr:1 row_mask:0xf bank_mask:0xf bound_ctrl:1
	v_add_f32_dpp v170, v170, v170 row_shr:1 row_mask:0xf bank_mask:0xf bound_ctrl:1
	v_add_f32_dpp v171, v171, v171 row_shr:1 row_mask:0xf bank_mask:0xf bound_ctrl:1
	v_add_f32_dpp v172, v172, v172 row_shr:1 row_mask:0xf bank_mask:0xf bound_ctrl:1
	v_add_f32_dpp v173, v173, v173 row_shr:1 row_mask:0xf bank_mask:0xf bound_ctrl:1
	v_add_f32_dpp v166, v166, v166 row_shr:2 row_mask:0xf bank_mask:0xf bound_ctrl:1
	v_add_f32_dpp v167, v167, v167 row_shr:2 row_mask:0xf bank_mask:0xf bound_ctrl:1
	v_add_f32_dpp v168, v168, v168 row_shr:2 row_mask:0xf bank_mask:0xf bound_ctrl:1
	v_add_f32_dpp v169, v169, v169 row_shr:2 row_mask:0xf bank_mask:0xf bound_ctrl:1
	v_add_f32_dpp v170, v170, v170 row_shr:2 row_mask:0xf bank_mask:0xf bound_ctrl:1
	v_add_f32_dpp v171, v171, v171 row_shr:2 row_mask:0xf bank_mask:0xf bound_ctrl:1
	v_add_f32_dpp v172, v172, v172 row_shr:2 row_mask:0xf bank_mask:0xf bound_ctrl:1
	v_add_f32_dpp v173, v173, v173 row_shr:2 row_mask:0xf bank_mask:0xf bound_ctrl:1
	v_add_f32_dpp v166, v166, v166 row_shr:4 row_mask:0xf bank_mask:0xf bound_ctrl:1
	v_add_f32_dpp v167, v167, v167 row_shr:4 row_mask:0xf bank_mask:0xf bound_ctrl:1
	v_add_f32_dpp v168, v168, v168 row_shr:4 row_mask:0xf bank_mask:0xf bound_ctrl:1
	v_add_f32_dpp v169, v169, v169 row_shr:4 row_mask:0xf bank_mask:0xf bound_ctrl:1
	v_add_f32_dpp v170, v170, v170 row_shr:4 row_mask:0xf bank_mask:0xf bound_ctrl:1
	v_add_f32_dpp v171, v171, v171 row_shr:4 row_mask:0xf bank_mask:0xf bound_ctrl:1
	v_add_f32_dpp v172, v172, v172 row_shr:4 row_mask:0xf bank_mask:0xf bound_ctrl:1
	v_add_f32_dpp v173, v173, v173 row_shr:4 row_mask:0xf bank_mask:0xf bound_ctrl:1
	v_add_f32_dpp v166, v166, v166 row_shr:8 row_mask:0xf bank_mask:0xf bound_ctrl:1
	v_add_f32_dpp v167, v167, v167 row_shr:8 row_mask:0xf bank_mask:0xf bound_ctrl:1
	v_add_f32_dpp v168, v168, v168 row_shr:8 row_mask:0xf bank_mask:0xf bound_ctrl:1
	v_add_f32_dpp v169, v169, v169 row_shr:8 row_mask:0xf bank_mask:0xf bound_ctrl:1
	v_add_f32_dpp v170, v170, v170 row_shr:8 row_mask:0xf bank_mask:0xf bound_ctrl:1
	v_add_f32_dpp v171, v171, v171 row_shr:8 row_mask:0xf bank_mask:0xf bound_ctrl:1
	v_add_f32_dpp v172, v172, v172 row_shr:8 row_mask:0xf bank_mask:0xf bound_ctrl:1
	v_add_f32_dpp v173, v173, v173 row_shr:8 row_mask:0xf bank_mask:0xf bound_ctrl:1
	v_add_f32_dpp v166, v158, v166 row_newbcast:15 row_mask:0xf bank_mask:0xf bound_ctrl:1
	v_add_f32_dpp v167, v159, v167 row_newbcast:15 row_mask:0xf bank_mask:0xf bound_ctrl:1
	v_add_f32_dpp v168, v160, v168 row_newbcast:15 row_mask:0xf bank_mask:0xf bound_ctrl:1
	v_add_f32_dpp v169, v161, v169 row_newbcast:15 row_mask:0xf bank_mask:0xf bound_ctrl:1
	v_add_f32_dpp v170, v162, v170 row_newbcast:15 row_mask:0xf bank_mask:0xf bound_ctrl:1
	v_add_f32_dpp v171, v163, v171 row_newbcast:15 row_mask:0xf bank_mask:0xf bound_ctrl:1
	v_add_f32_dpp v172, v164, v172 row_newbcast:15 row_mask:0xf bank_mask:0xf bound_ctrl:1
	v_add_f32_dpp v173, v165, v173 row_newbcast:15 row_mask:0xf bank_mask:0xf bound_ctrl:1
	v_exp_f32_e64 v174, -v166
	v_exp_f32_e64 v175, -v167
	v_exp_f32_e64 v176, -v168
	v_exp_f32_e64 v177, -v169
	v_exp_f32_e64 v178, -v170
	v_exp_f32_e64 v179, -v171
	v_exp_f32_e64 v180, -v172
	v_exp_f32_e64 v181, -v173
	v_pk_mul_f32 v[182:183], v[50:51], s[84:85] op_sel_hi:[1,0]
	v_pk_mul_f32 v[184:185], v[52:53], s[84:85] op_sel_hi:[1,0]
	v_pk_mul_f32 v[186:187], v[18:19], s[84:85] op_sel_hi:[1,0]
	v_pk_mul_f32 v[188:189], v[20:21], s[84:85] op_sel_hi:[1,0]
	v_exp_f32_e32 v182, v182
	v_exp_f32_e32 v183, v183
	v_exp_f32_e32 v184, v184
	v_exp_f32_e32 v185, v185
	v_exp_f32_e32 v186, v186
	v_exp_f32_e32 v187, v187
	v_exp_f32_e32 v188, v188
	v_exp_f32_e32 v189, v189
	v_pk_add_f32 v[182:183], v[182:183], s[86:87] op_sel_hi:[1,0]
	v_pk_add_f32 v[184:185], v[184:185], s[86:87] op_sel_hi:[1,0]
	v_pk_add_f32 v[186:187], v[186:187], s[86:87] op_sel_hi:[1,0]
	v_pk_add_f32 v[188:189], v[188:189], s[86:87] op_sel_hi:[1,0]
	v_pk_mul_f32 v[182:183], v[182:183], v[174:175]
	v_pk_mul_f32 v[184:185], v[184:185], v[176:177]
	v_pk_mul_f32 v[186:187], v[186:187], v[178:179]
	v_pk_mul_f32 v[188:189], v[188:189], v[180:181]
	v_rcp_f32_e32 v182, v182
	v_rcp_f32_e32 v183, v183
	v_rcp_f32_e32 v184, v184
	v_rcp_f32_e32 v185, v185
	v_rcp_f32_e32 v186, v186
	v_rcp_f32_e32 v187, v187
	v_rcp_f32_e32 v188, v188
	v_rcp_f32_e32 v189, v189
	v_pk_add_f32 v[150:151], v[150:151], s[86:87] op_sel_hi:[1,0] neg_lo:[1,0] neg_hi:[1,0]
	v_pk_add_f32 v[152:153], v[152:153], s[86:87] op_sel_hi:[1,0] neg_lo:[1,0] neg_hi:[1,0]
	v_pk_add_f32 v[154:155], v[154:155], s[86:87] op_sel_hi:[1,0] neg_lo:[1,0] neg_hi:[1,0]
	v_pk_add_f32 v[156:157], v[156:157], s[86:87] op_sel_hi:[1,0] neg_lo:[1,0] neg_hi:[1,0]
	v_pk_mul_f32 v[150:151], v[150:151], v[174:175]
	v_pk_mul_f32 v[152:153], v[152:153], v[176:177]
	v_pk_mul_f32 v[154:155], v[154:155], v[178:179]
	v_pk_mul_f32 v[156:157], v[156:157], v[180:181]
	v_pk_mul_f32 v[182:183], v[50:51], v[182:183]
	v_pk_mul_f32 v[184:185], v[52:53], v[184:185]
	v_pk_mul_f32 v[186:187], v[18:19], v[186:187]
	v_pk_mul_f32 v[188:189], v[20:21], v[188:189]
	v_cvt_pk_bf16_f32 v174, v182, v183
	v_cvt_pk_bf16_f32 v175, v184, v185
	v_cvt_pk_bf16_f32 v176, v186, v187
	v_cvt_pk_bf16_f32 v177, v188, v189
	v_cvt_pk_bf16_f32 v178, v150, v151
	v_cvt_pk_bf16_f32 v179, v152, v153
	v_cvt_pk_bf16_f32 v180, v154, v155
	v_cvt_pk_bf16_f32 v181, v156, v157
	ds_bpermute_b32 v190, v148, v174
	ds_bpermute_b32 v191, v148, v175
	ds_bpermute_b32 v192, v148, v176
	ds_bpermute_b32 v193, v148, v177
	ds_bpermute_b32 v194, v148, v178
	ds_bpermute_b32 v195, v148, v179
	ds_bpermute_b32 v196, v148, v180
	ds_bpermute_b32 v197, v148, v181
	v_pk_mul_f32 v[150:151], v[58:59], s[84:85] op_sel_hi:[1,0]
	v_pk_mul_f32 v[152:153], v[60:61], s[84:85] op_sel_hi:[1,0]
	v_pk_mul_f32 v[154:155], v[26:27], s[84:85] op_sel_hi:[1,0]
	v_pk_mul_f32 v[156:157], v[28:29], s[84:85] op_sel_hi:[1,0]
	v_exp_f32_e32 v150, v150
	v_exp_f32_e32 v151, v151
	v_exp_f32_e32 v152, v152
	v_exp_f32_e32 v153, v153
	v_exp_f32_e32 v154, v154
	v_exp_f32_e32 v155, v155
	v_exp_f32_e32 v156, v156
	v_exp_f32_e32 v157, v157
	v_pk_add_f32 v[150:151], v[150:151], s[86:87] op_sel_hi:[1,0]
	v_pk_add_f32 v[152:153], v[152:153], s[86:87] op_sel_hi:[1,0]
	v_pk_add_f32 v[154:155], v[154:155], s[86:87] op_sel_hi:[1,0]
	v_pk_add_f32 v[156:157], v[156:157], s[86:87] op_sel_hi:[1,0]
	v_rcp_f32_e32 v150, v150
	v_rcp_f32_e32 v151, v151
	v_rcp_f32_e32 v152, v152
	v_rcp_f32_e32 v153, v153
	v_rcp_f32_e32 v154, v154
	v_rcp_f32_e32 v155, v155
	v_rcp_f32_e32 v156, v156
	v_rcp_f32_e32 v157, v157
	v_add_u32_e32 v220, 16, v4
	v_ashrrev_i32_e32 v221, 31, v220
	v_lshlrev_b64 v[222:223], 12, v[220:221]
	v_lshlrev_b64 v[224:225], 11, v[220:221]
	v_lshl_add_u64 v[222:223], v[142:143], 0, v[222:223]
	v_lshl_add_u64 v[224:225], v[144:145], 0, v[224:225]
	s_waitcnt lgkmcnt(0)
	global_store_dwordx4 v[222:223], v[190:193], off nt
	global_store_dwordx4 v[224:225], v[194:197], off nt
	v_pk_add_f32 v[174:175], v[138:139], s[86:87] op_sel_hi:[1,0] neg_lo:[1,0] neg_hi:[1,0]
	v_pk_add_f32 v[176:177], v[140:141], s[86:87] op_sel_hi:[1,0] neg_lo:[1,0] neg_hi:[1,0]
	v_pk_add_f32 v[178:179], v[134:135], s[86:87] op_sel_hi:[1,0] neg_lo:[1,0] neg_hi:[1,0]
	v_pk_add_f32 v[180:181], v[136:137], s[86:87] op_sel_hi:[1,0] neg_lo:[1,0] neg_hi:[1,0]
	v_pk_fma_f32 v[150:151], v[150:151], v[174:175], v[138:139]
	v_pk_fma_f32 v[152:153], v[152:153], v[176:177], v[140:141]
	v_pk_fma_f32 v[154:155], v[154:155], v[178:179], v[134:135]
	v_pk_fma_f32 v[156:157], v[156:157], v[180:181], v[136:137]
	v_log_f32_e32 v158, v150
	v_log_f32_e32 v159, v151
	v_log_f32_e32 v160, v152
	v_log_f32_e32 v161, v153
	v_log_f32_e32 v162, v154
	v_log_f32_e32 v163, v155
	v_log_f32_e32 v164, v156
	v_log_f32_e32 v165, v157
	v_add_f32_dpp v158, v158, v158 row_shr:1 row_mask:0xf bank_mask:0xf bound_ctrl:1
	v_add_f32_dpp v159, v159, v159 row_shr:1 row_mask:0xf bank_mask:0xf bound_ctrl:1
	v_add_f32_dpp v160, v160, v160 row_shr:1 row_mask:0xf bank_mask:0xf bound_ctrl:1
	v_add_f32_dpp v161, v161, v161 row_shr:1 row_mask:0xf bank_mask:0xf bound_ctrl:1
	v_add_f32_dpp v162, v162, v162 row_shr:1 row_mask:0xf bank_mask:0xf bound_ctrl:1
	v_add_f32_dpp v163, v163, v163 row_shr:1 row_mask:0xf bank_mask:0xf bound_ctrl:1
	v_add_f32_dpp v164, v164, v164 row_shr:1 row_mask:0xf bank_mask:0xf bound_ctrl:1
	v_add_f32_dpp v165, v165, v165 row_shr:1 row_mask:0xf bank_mask:0xf bound_ctrl:1
	v_add_f32_dpp v158, v158, v158 row_shr:2 row_mask:0xf bank_mask:0xf bound_ctrl:1
	v_add_f32_dpp v159, v159, v159 row_shr:2 row_mask:0xf bank_mask:0xf bound_ctrl:1
	v_add_f32_dpp v160, v160, v160 row_shr:2 row_mask:0xf bank_mask:0xf bound_ctrl:1
	v_add_f32_dpp v161, v161, v161 row_shr:2 row_mask:0xf bank_mask:0xf bound_ctrl:1
	v_add_f32_dpp v162, v162, v162 row_shr:2 row_mask:0xf bank_mask:0xf bound_ctrl:1
	v_add_f32_dpp v163, v163, v163 row_shr:2 row_mask:0xf bank_mask:0xf bound_ctrl:1
	v_add_f32_dpp v164, v164, v164 row_shr:2 row_mask:0xf bank_mask:0xf bound_ctrl:1
	v_add_f32_dpp v165, v165, v165 row_shr:2 row_mask:0xf bank_mask:0xf bound_ctrl:1
	v_add_f32_dpp v158, v158, v158 row_shr:4 row_mask:0xf bank_mask:0xf bound_ctrl:1
	v_add_f32_dpp v159, v159, v159 row_shr:4 row_mask:0xf bank_mask:0xf bound_ctrl:1
	v_add_f32_dpp v160, v160, v160 row_shr:4 row_mask:0xf bank_mask:0xf bound_ctrl:1
	v_add_f32_dpp v161, v161, v161 row_shr:4 row_mask:0xf bank_mask:0xf bound_ctrl:1
	v_add_f32_dpp v162, v162, v162 row_shr:4 row_mask:0xf bank_mask:0xf bound_ctrl:1
	v_add_f32_dpp v163, v163, v163 row_shr:4 row_mask:0xf bank_mask:0xf bound_ctrl:1
	v_add_f32_dpp v164, v164, v164 row_shr:4 row_mask:0xf bank_mask:0xf bound_ctrl:1
	v_add_f32_dpp v165, v165, v165 row_shr:4 row_mask:0xf bank_mask:0xf bound_ctrl:1
	v_add_f32_dpp v158, v158, v158 row_shr:8 row_mask:0xf bank_mask:0xf bound_ctrl:1
	v_add_f32_dpp v159, v159, v159 row_shr:8 row_mask:0xf bank_mask:0xf bound_ctrl:1
	v_add_f32_dpp v160, v160, v160 row_shr:8 row_mask:0xf bank_mask:0xf bound_ctrl:1
	v_add_f32_dpp v161, v161, v161 row_shr:8 row_mask:0xf bank_mask:0xf bound_ctrl:1
	v_add_f32_dpp v162, v162, v162 row_shr:8 row_mask:0xf bank_mask:0xf bound_ctrl:1
	v_add_f32_dpp v163, v163, v163 row_shr:8 row_mask:0xf bank_mask:0xf bound_ctrl:1
	v_add_f32_dpp v164, v164, v164 row_shr:8 row_mask:0xf bank_mask:0xf bound_ctrl:1
	v_add_f32_dpp v165, v165, v165 row_shr:8 row_mask:0xf bank_mask:0xf bound_ctrl:1
	v_add_f32_dpp v158, v166, v158 row_newbcast:15 row_mask:0xf bank_mask:0xf bound_ctrl:1
	v_add_f32_dpp v159, v167, v159 row_newbcast:15 row_mask:0xf bank_mask:0xf bound_ctrl:1
	v_add_f32_dpp v160, v168, v160 row_newbcast:15 row_mask:0xf bank_mask:0xf bound_ctrl:1
	v_add_f32_dpp v161, v169, v161 row_newbcast:15 row_mask:0xf bank_mask:0xf bound_ctrl:1
	v_add_f32_dpp v162, v170, v162 row_newbcast:15 row_mask:0xf bank_mask:0xf bound_ctrl:1
	v_add_f32_dpp v163, v171, v163 row_newbcast:15 row_mask:0xf bank_mask:0xf bound_ctrl:1
	v_add_f32_dpp v164, v172, v164 row_newbcast:15 row_mask:0xf bank_mask:0xf bound_ctrl:1
	v_add_f32_dpp v165, v173, v165 row_newbcast:15 row_mask:0xf bank_mask:0xf bound_ctrl:1
	v_exp_f32_e64 v174, -v158
	v_exp_f32_e64 v175, -v159
	v_exp_f32_e64 v176, -v160
	v_exp_f32_e64 v177, -v161
	v_exp_f32_e64 v178, -v162
	v_exp_f32_e64 v179, -v163
	v_exp_f32_e64 v180, -v164
	v_exp_f32_e64 v181, -v165
	v_pk_mul_f32 v[182:183], v[46:47], s[84:85] op_sel_hi:[1,0]
	v_pk_mul_f32 v[184:185], v[48:49], s[84:85] op_sel_hi:[1,0]
	v_pk_mul_f32 v[186:187], v[14:15], s[84:85] op_sel_hi:[1,0]
	v_pk_mul_f32 v[188:189], v[16:17], s[84:85] op_sel_hi:[1,0]
	v_exp_f32_e32 v182, v182
	v_exp_f32_e32 v183, v183
	v_exp_f32_e32 v184, v184
	v_exp_f32_e32 v185, v185
	v_exp_f32_e32 v186, v186
	v_exp_f32_e32 v187, v187
	v_exp_f32_e32 v188, v188
	v_exp_f32_e32 v189, v189
	v_pk_add_f32 v[182:183], v[182:183], s[86:87] op_sel_hi:[1,0]
	v_pk_add_f32 v[184:185], v[184:185], s[86:87] op_sel_hi:[1,0]
	v_pk_add_f32 v[186:187], v[186:187], s[86:87] op_sel_hi:[1,0]
	v_pk_add_f32 v[188:189], v[188:189], s[86:87] op_sel_hi:[1,0]
	v_pk_mul_f32 v[182:183], v[182:183], v[174:175]
	v_pk_mul_f32 v[184:185], v[184:185], v[176:177]
	v_pk_mul_f32 v[186:187], v[186:187], v[178:179]
	v_pk_mul_f32 v[188:189], v[188:189], v[180:181]
	v_rcp_f32_e32 v182, v182
	v_rcp_f32_e32 v183, v183
	v_rcp_f32_e32 v184, v184
	v_rcp_f32_e32 v185, v185
	v_rcp_f32_e32 v186, v186
	v_rcp_f32_e32 v187, v187
	v_rcp_f32_e32 v188, v188
	v_rcp_f32_e32 v189, v189
	v_pk_add_f32 v[150:151], v[150:151], s[86:87] op_sel_hi:[1,0] neg_lo:[1,0] neg_hi:[1,0]
	v_pk_add_f32 v[152:153], v[152:153], s[86:87] op_sel_hi:[1,0] neg_lo:[1,0] neg_hi:[1,0]
	v_pk_add_f32 v[154:155], v[154:155], s[86:87] op_sel_hi:[1,0] neg_lo:[1,0] neg_hi:[1,0]
	v_pk_add_f32 v[156:157], v[156:157], s[86:87] op_sel_hi:[1,0] neg_lo:[1,0] neg_hi:[1,0]
	v_pk_mul_f32 v[150:151], v[150:151], v[174:175]
	v_pk_mul_f32 v[152:153], v[152:153], v[176:177]
	v_pk_mul_f32 v[154:155], v[154:155], v[178:179]
	v_pk_mul_f32 v[156:157], v[156:157], v[180:181]
	v_pk_mul_f32 v[182:183], v[46:47], v[182:183]
	v_pk_mul_f32 v[184:185], v[48:49], v[184:185]
	v_pk_mul_f32 v[186:187], v[14:15], v[186:187]
	v_pk_mul_f32 v[188:189], v[16:17], v[188:189]
	v_cvt_pk_bf16_f32 v174, v182, v183
	v_cvt_pk_bf16_f32 v175, v184, v185
	v_cvt_pk_bf16_f32 v176, v186, v187
	v_cvt_pk_bf16_f32 v177, v188, v189
	v_cvt_pk_bf16_f32 v178, v150, v151
	v_cvt_pk_bf16_f32 v179, v152, v153
	v_cvt_pk_bf16_f32 v180, v154, v155
	v_cvt_pk_bf16_f32 v181, v156, v157
	ds_bpermute_b32 v190, v148, v174
	ds_bpermute_b32 v191, v148, v175
	ds_bpermute_b32 v192, v148, v176
	ds_bpermute_b32 v193, v148, v177
	ds_bpermute_b32 v194, v148, v178
	ds_bpermute_b32 v195, v148, v179
	ds_bpermute_b32 v196, v148, v180
	ds_bpermute_b32 v197, v148, v181
	v_pk_mul_f32 v[150:151], v[54:55], s[84:85] op_sel_hi:[1,0]
	v_pk_mul_f32 v[152:153], v[56:57], s[84:85] op_sel_hi:[1,0]
	v_pk_mul_f32 v[154:155], v[22:23], s[84:85] op_sel_hi:[1,0]
	v_pk_mul_f32 v[156:157], v[24:25], s[84:85] op_sel_hi:[1,0]
	v_exp_f32_e32 v150, v150
	v_exp_f32_e32 v151, v151
	v_exp_f32_e32 v152, v152
	v_exp_f32_e32 v153, v153
	v_exp_f32_e32 v154, v154
	v_exp_f32_e32 v155, v155
	v_exp_f32_e32 v156, v156
	v_exp_f32_e32 v157, v157
	v_pk_add_f32 v[150:151], v[150:151], s[86:87] op_sel_hi:[1,0]
	v_pk_add_f32 v[152:153], v[152:153], s[86:87] op_sel_hi:[1,0]
	v_pk_add_f32 v[154:155], v[154:155], s[86:87] op_sel_hi:[1,0]
	v_pk_add_f32 v[156:157], v[156:157], s[86:87] op_sel_hi:[1,0]
	v_rcp_f32_e32 v150, v150
	v_rcp_f32_e32 v151, v151
	v_rcp_f32_e32 v152, v152
	v_rcp_f32_e32 v153, v153
	v_rcp_f32_e32 v154, v154
	v_rcp_f32_e32 v155, v155
	v_rcp_f32_e32 v156, v156
	v_rcp_f32_e32 v157, v157
	v_add_u32_e32 v220, 32, v4
	v_ashrrev_i32_e32 v221, 31, v220
	v_lshlrev_b64 v[222:223], 12, v[220:221]
	v_lshlrev_b64 v[224:225], 11, v[220:221]
	v_lshl_add_u64 v[222:223], v[142:143], 0, v[222:223]
	v_lshl_add_u64 v[224:225], v[144:145], 0, v[224:225]
	s_waitcnt lgkmcnt(0)
	global_store_dwordx4 v[222:223], v[190:193], off nt
	global_store_dwordx4 v[224:225], v[194:197], off nt
	v_pk_add_f32 v[174:175], v[138:139], s[86:87] op_sel_hi:[1,0] neg_lo:[1,0] neg_hi:[1,0]
	v_pk_add_f32 v[176:177], v[140:141], s[86:87] op_sel_hi:[1,0] neg_lo:[1,0] neg_hi:[1,0]
	v_pk_add_f32 v[178:179], v[134:135], s[86:87] op_sel_hi:[1,0] neg_lo:[1,0] neg_hi:[1,0]
	v_pk_add_f32 v[180:181], v[136:137], s[86:87] op_sel_hi:[1,0] neg_lo:[1,0] neg_hi:[1,0]
	v_pk_fma_f32 v[150:151], v[150:151], v[174:175], v[138:139]
	v_pk_fma_f32 v[152:153], v[152:153], v[176:177], v[140:141]
	v_pk_fma_f32 v[154:155], v[154:155], v[178:179], v[134:135]
	v_pk_fma_f32 v[156:157], v[156:157], v[180:181], v[136:137]
	v_log_f32_e32 v166, v150
	v_log_f32_e32 v167, v151
	v_log_f32_e32 v168, v152
	v_log_f32_e32 v169, v153
	v_log_f32_e32 v170, v154
	v_log_f32_e32 v171, v155
	v_log_f32_e32 v172, v156
	v_log_f32_e32 v173, v157
	v_add_f32_dpp v166, v166, v166 row_shr:1 row_mask:0xf bank_mask:0xf bound_ctrl:1
	v_add_f32_dpp v167, v167, v167 row_shr:1 row_mask:0xf bank_mask:0xf bound_ctrl:1
	v_add_f32_dpp v168, v168, v168 row_shr:1 row_mask:0xf bank_mask:0xf bound_ctrl:1
	v_add_f32_dpp v169, v169, v169 row_shr:1 row_mask:0xf bank_mask:0xf bound_ctrl:1
	v_add_f32_dpp v170, v170, v170 row_shr:1 row_mask:0xf bank_mask:0xf bound_ctrl:1
	v_add_f32_dpp v171, v171, v171 row_shr:1 row_mask:0xf bank_mask:0xf bound_ctrl:1
	v_add_f32_dpp v172, v172, v172 row_shr:1 row_mask:0xf bank_mask:0xf bound_ctrl:1
	v_add_f32_dpp v173, v173, v173 row_shr:1 row_mask:0xf bank_mask:0xf bound_ctrl:1
	v_add_f32_dpp v166, v166, v166 row_shr:2 row_mask:0xf bank_mask:0xf bound_ctrl:1
	v_add_f32_dpp v167, v167, v167 row_shr:2 row_mask:0xf bank_mask:0xf bound_ctrl:1
	v_add_f32_dpp v168, v168, v168 row_shr:2 row_mask:0xf bank_mask:0xf bound_ctrl:1
	v_add_f32_dpp v169, v169, v169 row_shr:2 row_mask:0xf bank_mask:0xf bound_ctrl:1
	v_add_f32_dpp v170, v170, v170 row_shr:2 row_mask:0xf bank_mask:0xf bound_ctrl:1
	v_add_f32_dpp v171, v171, v171 row_shr:2 row_mask:0xf bank_mask:0xf bound_ctrl:1
	v_add_f32_dpp v172, v172, v172 row_shr:2 row_mask:0xf bank_mask:0xf bound_ctrl:1
	v_add_f32_dpp v173, v173, v173 row_shr:2 row_mask:0xf bank_mask:0xf bound_ctrl:1
	v_add_f32_dpp v166, v166, v166 row_shr:4 row_mask:0xf bank_mask:0xf bound_ctrl:1
	v_add_f32_dpp v167, v167, v167 row_shr:4 row_mask:0xf bank_mask:0xf bound_ctrl:1
	v_add_f32_dpp v168, v168, v168 row_shr:4 row_mask:0xf bank_mask:0xf bound_ctrl:1
	v_add_f32_dpp v169, v169, v169 row_shr:4 row_mask:0xf bank_mask:0xf bound_ctrl:1
	v_add_f32_dpp v170, v170, v170 row_shr:4 row_mask:0xf bank_mask:0xf bound_ctrl:1
	v_add_f32_dpp v171, v171, v171 row_shr:4 row_mask:0xf bank_mask:0xf bound_ctrl:1
	v_add_f32_dpp v172, v172, v172 row_shr:4 row_mask:0xf bank_mask:0xf bound_ctrl:1
	v_add_f32_dpp v173, v173, v173 row_shr:4 row_mask:0xf bank_mask:0xf bound_ctrl:1
	v_add_f32_dpp v166, v166, v166 row_shr:8 row_mask:0xf bank_mask:0xf bound_ctrl:1
	v_add_f32_dpp v167, v167, v167 row_shr:8 row_mask:0xf bank_mask:0xf bound_ctrl:1
	v_add_f32_dpp v168, v168, v168 row_shr:8 row_mask:0xf bank_mask:0xf bound_ctrl:1
	v_add_f32_dpp v169, v169, v169 row_shr:8 row_mask:0xf bank_mask:0xf bound_ctrl:1
	v_add_f32_dpp v170, v170, v170 row_shr:8 row_mask:0xf bank_mask:0xf bound_ctrl:1
	v_add_f32_dpp v171, v171, v171 row_shr:8 row_mask:0xf bank_mask:0xf bound_ctrl:1
	v_add_f32_dpp v172, v172, v172 row_shr:8 row_mask:0xf bank_mask:0xf bound_ctrl:1
	v_add_f32_dpp v173, v173, v173 row_shr:8 row_mask:0xf bank_mask:0xf bound_ctrl:1
	v_add_f32_dpp v166, v158, v166 row_newbcast:15 row_mask:0xf bank_mask:0xf bound_ctrl:1
	v_add_f32_dpp v167, v159, v167 row_newbcast:15 row_mask:0xf bank_mask:0xf bound_ctrl:1
	v_add_f32_dpp v168, v160, v168 row_newbcast:15 row_mask:0xf bank_mask:0xf bound_ctrl:1
	v_add_f32_dpp v169, v161, v169 row_newbcast:15 row_mask:0xf bank_mask:0xf bound_ctrl:1
	v_add_f32_dpp v170, v162, v170 row_newbcast:15 row_mask:0xf bank_mask:0xf bound_ctrl:1
	v_add_f32_dpp v171, v163, v171 row_newbcast:15 row_mask:0xf bank_mask:0xf bound_ctrl:1
	v_add_f32_dpp v172, v164, v172 row_newbcast:15 row_mask:0xf bank_mask:0xf bound_ctrl:1
	v_add_f32_dpp v173, v165, v173 row_newbcast:15 row_mask:0xf bank_mask:0xf bound_ctrl:1
	v_exp_f32_e64 v174, -v166
	v_exp_f32_e64 v175, -v167
	v_exp_f32_e64 v176, -v168
	v_exp_f32_e64 v177, -v169
	v_exp_f32_e64 v178, -v170
	v_exp_f32_e64 v179, -v171
	v_exp_f32_e64 v180, -v172
	v_exp_f32_e64 v181, -v173
	v_pk_mul_f32 v[182:183], v[42:43], s[84:85] op_sel_hi:[1,0]
	v_pk_mul_f32 v[184:185], v[44:45], s[84:85] op_sel_hi:[1,0]
	v_pk_mul_f32 v[186:187], v[10:11], s[84:85] op_sel_hi:[1,0]
	v_pk_mul_f32 v[188:189], v[12:13], s[84:85] op_sel_hi:[1,0]
	v_exp_f32_e32 v182, v182
	v_exp_f32_e32 v183, v183
	v_exp_f32_e32 v184, v184
	v_exp_f32_e32 v185, v185
	v_exp_f32_e32 v186, v186
	v_exp_f32_e32 v187, v187
	v_exp_f32_e32 v188, v188
	v_exp_f32_e32 v189, v189
	v_pk_add_f32 v[182:183], v[182:183], s[86:87] op_sel_hi:[1,0]
	v_pk_add_f32 v[184:185], v[184:185], s[86:87] op_sel_hi:[1,0]
	v_pk_add_f32 v[186:187], v[186:187], s[86:87] op_sel_hi:[1,0]
	v_pk_add_f32 v[188:189], v[188:189], s[86:87] op_sel_hi:[1,0]
	v_pk_mul_f32 v[182:183], v[182:183], v[174:175]
	v_pk_mul_f32 v[184:185], v[184:185], v[176:177]
	v_pk_mul_f32 v[186:187], v[186:187], v[178:179]
	v_pk_mul_f32 v[188:189], v[188:189], v[180:181]
	v_rcp_f32_e32 v182, v182
	v_rcp_f32_e32 v183, v183
	v_rcp_f32_e32 v184, v184
	v_rcp_f32_e32 v185, v185
	v_rcp_f32_e32 v186, v186
	v_rcp_f32_e32 v187, v187
	v_rcp_f32_e32 v188, v188
	v_rcp_f32_e32 v189, v189
	v_pk_add_f32 v[150:151], v[150:151], s[86:87] op_sel_hi:[1,0] neg_lo:[1,0] neg_hi:[1,0]
	v_pk_add_f32 v[152:153], v[152:153], s[86:87] op_sel_hi:[1,0] neg_lo:[1,0] neg_hi:[1,0]
	v_pk_add_f32 v[154:155], v[154:155], s[86:87] op_sel_hi:[1,0] neg_lo:[1,0] neg_hi:[1,0]
	v_pk_add_f32 v[156:157], v[156:157], s[86:87] op_sel_hi:[1,0] neg_lo:[1,0] neg_hi:[1,0]
	v_pk_mul_f32 v[150:151], v[150:151], v[174:175]
	v_pk_mul_f32 v[152:153], v[152:153], v[176:177]
	v_pk_mul_f32 v[154:155], v[154:155], v[178:179]
	v_pk_mul_f32 v[156:157], v[156:157], v[180:181]
	v_pk_mul_f32 v[182:183], v[42:43], v[182:183]
	v_pk_mul_f32 v[184:185], v[44:45], v[184:185]
	v_pk_mul_f32 v[186:187], v[10:11], v[186:187]
	v_pk_mul_f32 v[188:189], v[12:13], v[188:189]
	v_cvt_pk_bf16_f32 v174, v182, v183
	v_cvt_pk_bf16_f32 v175, v184, v185
	v_cvt_pk_bf16_f32 v176, v186, v187
	v_cvt_pk_bf16_f32 v177, v188, v189
	v_cvt_pk_bf16_f32 v178, v150, v151
	v_cvt_pk_bf16_f32 v179, v152, v153
	v_cvt_pk_bf16_f32 v180, v154, v155
	v_cvt_pk_bf16_f32 v181, v156, v157
	ds_bpermute_b32 v190, v148, v174
	ds_bpermute_b32 v191, v148, v175
	ds_bpermute_b32 v192, v148, v176
	ds_bpermute_b32 v193, v148, v177
	ds_bpermute_b32 v194, v148, v178
	ds_bpermute_b32 v195, v148, v179
	ds_bpermute_b32 v196, v148, v180
	ds_bpermute_b32 v197, v148, v181
	v_add_u32_e32 v220, 48, v4
	v_ashrrev_i32_e32 v221, 31, v220
	v_lshlrev_b64 v[222:223], 12, v[220:221]
	v_lshlrev_b64 v[224:225], 11, v[220:221]
	v_lshl_add_u64 v[222:223], v[142:143], 0, v[222:223]
	v_lshl_add_u64 v[224:225], v[144:145], 0, v[224:225]
	s_waitcnt lgkmcnt(0)
	global_store_dwordx4 v[222:223], v[190:193], off nt
	global_store_dwordx4 v[224:225], v[194:197], off nt
	s_and_saveexec_b64 s[0:1], s[90:91]
	s_ashr_i32 s2, s43, 6
	s_ashr_i32 s3, s2, 31
	s_lshl_b64 s[2:3], s[2:3], 12
	v_lshl_add_u64 v[222:223], v[146:147], 0, s[2:3]
	global_store_dwordx4 v[222:223], v[166:169], off
	global_store_dwordx4 v[222:223], v[170:173], off offset:16
